# combo20 + attention PV blocks read their four LDS fragments up front + scan o stores use one SGPR base per chunk instead of 32 64-bit VALU adds
# speedup vs baseline: 1.0047x; 1.0047x over previous
; #define LAS __attribute__((address_space(3)))
; __device__ __forceinline__ f32x4 mfma16(const bf16x8& a, const bf16x8& b, const f32x4& c) { return __builtin_amdgcn_mfma_f32_16x16x32_bf16(a, b, c, 0, 0, 0); }
; __device__ __forceinline__ void attn_items(const Params& p, LAS unsigned char* lds, int ai0, int aistride) {
;     ...
;                 mx = fmaxf(mx, __shfl_xor(mx, 16)); mx = fmaxf(mx, __shfl_xor(mx, 32));
;                 float l = 0.f;
; #pragma unroll
;                 for (int kt = 0; kt < 12; ++kt)
; #pragma unroll
;                     for (int jj = 0; jj < 4; ++jj) { const float pv = __expf(s[kt][jj] - mx); s[kt][jj] = pv; l += pv; }
;                 l += __shfl_xor(l, 16); l += __shfl_xor(l, 32);
;                 l += __expf(sink - mx);
;                 const float inv = __builtin_amdgcn_rcpf(l);
;                 f32x4 o[4];
; #pragma unroll
;                 for (int dt = 0; dt < 4; ++dt) o[dt] = (f32x4){0.f, 0.f, 0.f, 0.f};
; #pragma unroll
;                 for (int u = 0; u < 6; ++u) {
;                     if (2 * u < nkt) {
;                         const bf16x8 Pf = pack8(s[2 * u], s[2 * u + 1]);
; #pragma unroll
;                         for (int dt = 0; dt < 4; ++dt) {
;                             const u32x2 lo = *(const LAS u32x2*)(Vt_s + (16 * dt + fr) * 200 + 32 * u + 4 * fq), hi = *(const LAS u32x2*)(Vt_s + (16 * dt + fr) * 200 + 32 * u + 16 + 4 * fq);
;                             o[dt] = mfma16(cat8(lo, hi), Pf, o[dt]);
.LBB0_567:
	ds_bpermute_b32 v3, v27, v29
	v_max_f32_e32 v4, v29, v29
	s_and_b64 vcc, exec, s[4:5]
	s_waitcnt lgkmcnt(0)
	v_max_f32_e32 v3, v3, v3
	v_max_f32_e32 v3, v4, v3
	ds_bpermute_b32 v4, v16, v3
	s_waitcnt lgkmcnt(0)
	v_max_f32_e32 v4, v4, v4
	v_max_f32_e32 v29, v3, v4
	v_sub_f32_e32 v4, v74, v29
	v_sub_f32_e32 v7, v66, v29
	v_mul_f32_e32 v4, 0x3fb8aa3b, v4
	v_exp_f32_e32 v15, v4
	v_mul_f32_e32 v4, 0x3fb8aa3b, v7
	v_exp_f32_e32 v97, v4
	v_sub_f32_e32 v4, v71, v29
	v_mul_f32_e32 v4, 0x3fb8aa3b, v4
	v_exp_f32_e32 v98, v4
	v_sub_f32_e32 v4, v67, v29
	v_mul_f32_e32 v4, 0x3fb8aa3b, v4
	v_exp_f32_e32 v99, v4
	v_sub_f32_e32 v4, v65, v29
	v_mul_f32_e32 v4, 0x3fb8aa3b, v4
	v_exp_f32_e32 v100, v4
	v_sub_f32_e32 v4, v68, v29
	v_mul_f32_e32 v4, 0x3fb8aa3b, v4
	v_exp_f32_e32 v108, v4
	v_sub_f32_e32 v4, v79, v29
	v_mul_f32_e32 v4, 0x3fb8aa3b, v4
	v_exp_f32_e32 v109, v4
	v_sub_f32_e32 v4, v75, v29
	v_mul_f32_e32 v4, 0x3fb8aa3b, v4
	v_exp_f32_e32 v110, v4
	v_sub_f32_e32 v4, v72, v29
	v_mul_f32_e32 v4, 0x3fb8aa3b, v4
	v_exp_f32_e32 v111, v4
	v_sub_f32_e32 v4, v76, v29
	v_mul_f32_e32 v4, 0x3fb8aa3b, v4
	v_exp_f32_e32 v112, v4
	v_sub_f32_e32 v4, v80, v29
	v_mul_f32_e32 v4, 0x3fb8aa3b, v4
	v_exp_f32_e32 v113, v4
	v_sub_f32_e32 v4, v77, v29
	v_mul_f32_e32 v4, 0x3fb8aa3b, v4
	v_exp_f32_e32 v114, v4
	v_sub_f32_e32 v4, v73, v29
	v_mul_f32_e32 v4, 0x3fb8aa3b, v4
	v_exp_f32_e32 v115, v4
	v_sub_f32_e32 v4, v12, v29
	v_mul_f32_e32 v4, 0x3fb8aa3b, v4
	v_exp_f32_e32 v76, v4
	v_sub_f32_e32 v4, v13, v29
	v_mul_f32_e32 v4, 0x3fb8aa3b, v4
	v_sub_f32_e32 v3, v78, v29
	v_exp_f32_e32 v78, v4
	v_sub_f32_e32 v4, v10, v29
	v_mul_f32_e32 v4, 0x3fb8aa3b, v4
	v_exp_f32_e32 v90, v4
	v_sub_f32_e32 v4, v11, v29
	v_mul_f32_e32 v4, 0x3fb8aa3b, v4
	v_exp_f32_e32 v91, v4
	v_sub_f32_e32 v4, v8, v29
	v_mul_f32_e32 v4, 0x3fb8aa3b, v4
	v_exp_f32_e32 v92, v4
	v_sub_f32_e32 v4, v9, v29
	v_mul_f32_e32 v4, 0x3fb8aa3b, v4
	v_exp_f32_e32 v93, v4
	v_sub_f32_e32 v4, v30, v29
	v_mul_f32_e32 v3, 0x3fb8aa3b, v3
	v_mul_f32_e32 v4, 0x3fb8aa3b, v4
	v_sub_f32_e32 v5, v70, v29
	v_exp_f32_e32 v14, v3
	v_exp_f32_e32 v94, v4
	v_sub_f32_e32 v4, v31, v29
	v_sub_f32_e32 v6, v69, v29
	v_mul_f32_e32 v5, 0x3fb8aa3b, v5
	v_mul_f32_e32 v4, 0x3fb8aa3b, v4
	v_mul_f32_e32 v6, 0x3fb8aa3b, v6
	v_exp_f32_e32 v69, v5
	v_exp_f32_e32 v95, v4
	v_sub_f32_e32 v4, v36, v29
	v_exp_f32_e32 v96, v6
	v_mul_f32_e32 v4, 0x3fb8aa3b, v4
	v_add_f32_e32 v3, 0, v14
	v_exp_f32_e32 v66, v4
	v_sub_f32_e32 v4, v37, v29
	v_add_f32_e32 v3, v15, v3
	v_mul_f32_e32 v4, 0x3fb8aa3b, v4
	v_add_f32_e32 v3, v69, v3
	v_exp_f32_e32 v70, v4
	v_sub_f32_e32 v4, v34, v29
	v_add_f32_e32 v3, v96, v3
	v_mul_f32_e32 v4, 0x3fb8aa3b, v4
	v_add_f32_e32 v3, v97, v3
	v_exp_f32_e32 v72, v4
	v_sub_f32_e32 v4, v35, v29
	v_add_f32_e32 v3, v98, v3
	v_mul_f32_e32 v4, 0x3fb8aa3b, v4
	v_add_f32_e32 v3, v99, v3
	v_exp_f32_e32 v73, v4
	v_sub_f32_e32 v4, v32, v29
	v_add_f32_e32 v3, v100, v3
	v_mul_f32_e32 v4, 0x3fb8aa3b, v4
	v_add_f32_e32 v3, v108, v3
	v_exp_f32_e32 v74, v4
	v_sub_f32_e32 v4, v33, v29
	v_add_f32_e32 v3, v109, v3
	v_mul_f32_e32 v4, 0x3fb8aa3b, v4
	v_add_f32_e32 v3, v110, v3
	v_exp_f32_e32 v75, v4
	v_sub_f32_e32 v4, v38, v29
	v_add_f32_e32 v3, v111, v3
	v_mul_f32_e32 v4, 0x3fb8aa3b, v4
	v_add_f32_e32 v3, v112, v3
	v_exp_f32_e32 v77, v4
	v_sub_f32_e32 v4, v39, v29
	v_add_f32_e32 v3, v113, v3
	v_mul_f32_e32 v4, 0x3fb8aa3b, v4
	v_add_f32_e32 v3, v114, v3
	v_exp_f32_e32 v79, v4
	v_sub_f32_e32 v4, v42, v29
	v_add_f32_e32 v3, v115, v3
	v_mul_f32_e32 v4, 0x3fb8aa3b, v4
	v_add_f32_e32 v3, v76, v3
	v_exp_f32_e32 v38, v4
	v_sub_f32_e32 v4, v43, v29
	v_add_f32_e32 v3, v78, v3
	v_mul_f32_e32 v4, 0x3fb8aa3b, v4
	v_add_f32_e32 v3, v90, v3
	v_exp_f32_e32 v39, v4
	v_sub_f32_e32 v4, v40, v29
	v_add_f32_e32 v3, v91, v3
	v_mul_f32_e32 v4, 0x3fb8aa3b, v4
	v_add_f32_e32 v3, v92, v3
	v_exp_f32_e32 v40, v4
	v_sub_f32_e32 v4, v41, v29
	v_add_f32_e32 v3, v93, v3
	v_mul_f32_e32 v4, 0x3fb8aa3b, v4
	v_add_f32_e32 v3, v94, v3
	v_exp_f32_e32 v41, v4
	v_sub_f32_e32 v4, v81, v29
	v_add_f32_e32 v3, v95, v3
	v_mul_f32_e32 v4, 0x3fb8aa3b, v4
	v_add_f32_e32 v3, v66, v3
	v_exp_f32_e32 v42, v4
	v_sub_f32_e32 v4, v84, v29
	v_add_f32_e32 v3, v70, v3
	v_mul_f32_e32 v4, 0x3fb8aa3b, v4
	v_add_f32_e32 v3, v72, v3
	v_exp_f32_e32 v43, v4
	v_sub_f32_e32 v4, v83, v29
	v_add_f32_e32 v3, v73, v3
	v_mul_f32_e32 v4, 0x3fb8aa3b, v4
	v_add_f32_e32 v3, v74, v3
	v_exp_f32_e32 v68, v4
	v_sub_f32_e32 v4, v82, v29
	v_add_f32_e32 v3, v75, v3
	v_mul_f32_e32 v4, 0x3fb8aa3b, v4
	v_add_f32_e32 v3, v77, v3
	v_exp_f32_e32 v71, v4
	v_sub_f32_e32 v4, v89, v29
	v_add_f32_e32 v3, v79, v3
	v_mul_f32_e32 v4, 0x3fb8aa3b, v4
	v_add_f32_e32 v3, v38, v3
	v_exp_f32_e32 v32, v4
	v_sub_f32_e32 v4, v88, v29
	v_add_f32_e32 v3, v39, v3
	v_mul_f32_e32 v4, 0x3fb8aa3b, v4
	v_add_f32_e32 v3, v40, v3
	v_exp_f32_e32 v33, v4
	v_sub_f32_e32 v4, v87, v29
	v_add_f32_e32 v3, v41, v3
	v_mul_f32_e32 v4, 0x3fb8aa3b, v4
	v_add_f32_e32 v3, v42, v3
	v_exp_f32_e32 v34, v4
	v_sub_f32_e32 v4, v86, v29
	v_add_f32_e32 v3, v43, v3
	v_mul_f32_e32 v4, 0x3fb8aa3b, v4
	v_add_f32_e32 v3, v68, v3
	v_exp_f32_e32 v35, v4
	v_sub_f32_e32 v4, v85, v29
	v_add_f32_e32 v3, v71, v3
	v_mul_f32_e32 v4, 0x3fb8aa3b, v4
	v_sub_f32_e32 v2, v2, v29
	v_add_f32_e32 v3, v32, v3
	v_exp_f32_e32 v36, v4
	v_mul_f32_e32 v2, 0x3fb8aa3b, v2
	v_add_f32_e32 v3, v33, v3
	v_exp_f32_e32 v37, v2
	v_add_f32_e32 v2, v34, v3
	v_add_f32_e32 v2, v35, v2
	v_add_f32_e32 v2, v36, v2
	v_add_u32_e32 v67, 0x6800, v50
	v_add_f32_e32 v30, v37, v2
	ds_read2_b64 v[2:5], v67 offset0:128 offset1:132
	v_cvt_pk_bf16_f32 v7, v69, v96
	v_add_u32_e32 v65, 0x8000, v50
	v_add_u32_e32 v69, 0x9800, v50
	v_add_u32_e32 v82, 0xb000, v50
	ds_read2_b64 v[10:13], v65 offset0:160 offset1:164
	v_cvt_pk_bf16_f32 v8, v97, v98
	v_cvt_pk_bf16_f32 v9, v99, v100
	ds_read2_b64 v[84:87], v69 offset0:192 offset1:196
	ds_read2_b64 v[96:99], v82 offset0:224 offset1:228
	ds_read2_b64 v[100:103], v67 offset0:136 offset1:140
	v_sub_f32_e32 v1, v1, v29
	v_cvt_pk_bf16_f32 v6, v14, v15
	v_mul_f32_e32 v1, 0x3fb8aa3b, v1
	v_sub_f32_e32 v0, v0, v29
	s_waitcnt lgkmcnt(4)
; #define LAS __attribute__((address_space(3)))
; __device__ __forceinline__ f32x4 mfma16(const bf16x8& a, const bf16x8& b, const f32x4& c) { return __builtin_amdgcn_mfma_f32_16x16x32_bf16(a, b, c, 0, 0, 0); }
; __device__ __forceinline__ void attn_items(const Params& p, LAS unsigned char* lds, int ai0, int aistride) {
;     ...
;                 for (int u = 0; u < 6; ++u) {
;                     if (2 * u < nkt) {
;                         const bf16x8 Pf = pack8(s[2 * u], s[2 * u + 1]);
; #pragma unroll
;                         for (int dt = 0; dt < 4; ++dt) {
;                             const u32x2 lo = *(const LAS u32x2*)(Vt_s + (16 * dt + fr) * 200 + 32 * u + 4 * fq), hi = *(const LAS u32x2*)(Vt_s + (16 * dt + fr) * 200 + 32 * u + 16 + 4 * fq);
;                             o[dt] = mfma16(cat8(lo, hi), Pf, o[dt]);
;                         }
	v_mfma_f32_16x16x32_bf16 v[2:5], v[2:5], v[6:9], 0
	v_exp_f32_e32 v80, v1
	v_mul_f32_e32 v0, 0x3fb8aa3b, v0
	v_exp_f32_e32 v81, v0
	v_cvt_pk_bf16_f32 v108, v108, v109
	v_cvt_pk_bf16_f32 v109, v110, v111
	v_cvt_pk_bf16_f32 v110, v112, v113
	v_cvt_pk_bf16_f32 v111, v114, v115
	s_waitcnt lgkmcnt(3)
	v_mfma_f32_16x16x32_bf16 v[12:15], v[10:13], v[6:9], 0
	ds_read2_b64 v[104:107], v65 offset0:168 offset1:172
	s_waitcnt lgkmcnt(3)
	v_mfma_f32_16x16x32_bf16 v[84:87], v[84:87], v[6:9], 0
	s_waitcnt lgkmcnt(2)
	v_mfma_f32_16x16x32_bf16 v[96:99], v[96:99], v[6:9], 0
	s_waitcnt lgkmcnt(1)
	v_mfma_f32_16x16x32_bf16 v[8:11], v[100:103], v[108:111], v[2:5]
	ds_read2_b64 v[100:103], v82 offset0:232 offset1:236
	s_nop 1
	ds_read2_b64 v[0:3], v69 offset0:200 offset1:204
	v_add_f32_e32 v4, v80, v30
	v_add_f32_e32 v30, v81, v4
	ds_bpermute_b32 v27, v27, v30
	s_waitcnt lgkmcnt(3)
	v_mfma_f32_16x16x32_bf16 v[12:15], v[104:107], v[108:111], v[12:15]
	s_waitcnt lgkmcnt(0)
	v_add_f32_e32 v30, v30, v27
	ds_bpermute_b32 v31, v16, v30
	v_mfma_f32_16x16x32_bf16 v[4:7], v[0:3], v[108:111], v[84:87]
	v_mfma_f32_16x16x32_bf16 v[0:3], v[100:103], v[108:111], v[96:99]
	s_cbranch_vccnz .LBB0_571
	s_nop 0
	ds_read2_b64 v[84:87], v67 offset0:144 offset1:148
	ds_read2_b64 v[186:189], v65 offset0:176 offset1:180
	ds_read2_b64 v[190:193], v69 offset0:208 offset1:212
	ds_read2_b64 v[194:197], v82 offset0:240 offset1:244
	v_cvt_pk_bf16_f32 v88, v76, v78
	v_cvt_pk_bf16_f32 v89, v90, v91
	v_cvt_pk_bf16_f32 v90, v92, v93
	v_cvt_pk_bf16_f32 v91, v94, v95
	s_nop 1
	s_waitcnt lgkmcnt(3)
	v_mfma_f32_16x16x32_bf16 v[8:11], v[84:87], v[88:91], v[8:11]
	s_waitcnt lgkmcnt(2)
	v_mfma_f32_16x16x32_bf16 v[12:15], v[186:189], v[88:91], v[12:15]
	s_waitcnt lgkmcnt(1)
	v_mfma_f32_16x16x32_bf16 v[4:7], v[190:193], v[88:91], v[4:7]
	s_waitcnt lgkmcnt(0)
	v_mfma_f32_16x16x32_bf16 v[0:3], v[194:197], v[88:91], v[0:3]
	s_and_b64 vcc, exec, s[6:7]
	s_cbranch_vccz .LBB0_572

; #define LAS __attribute__((address_space(3)))
; __device__ __forceinline__ f32x4 mfma16(const bf16x8& a, const bf16x8& b, const f32x4& c) { return __builtin_amdgcn_mfma_f32_16x16x32_bf16(a, b, c, 0, 0, 0); }
; __device__ __forceinline__ void attn_items(const Params& p, LAS unsigned char* lds, int ai0, int aistride) {
;     ...
;                 for (int u = 0; u < 6; ++u) {
;                     if (2 * u < nkt) {
;                         const bf16x8 Pf = pack8(s[2 * u], s[2 * u + 1]);
; #pragma unroll
;                         for (int dt = 0; dt < 4; ++dt) {
;                             const u32x2 lo = *(const LAS u32x2*)(Vt_s + (16 * dt + fr) * 200 + 32 * u + 4 * fq), hi = *(const LAS u32x2*)(Vt_s + (16 * dt + fr) * 200 + 32 * u + 16 + 4 * fq);
;                             o[dt] = mfma16(cat8(lo, hi), Pf, o[dt]);
;                         }
.LBB0_570:
	ds_read2_b64 v[72:75], v67 offset0:160 offset1:164
	ds_read2_b64 v[186:189], v65 offset0:192 offset1:196
	ds_read2_b64 v[190:193], v69 offset0:224 offset1:228
	ds_read2_b64 v[194:197], v16 offset1:4
	v_cvt_pk_bf16_f32 v38, v38, v39
	v_cvt_pk_bf16_f32 v39, v40, v41
	v_cvt_pk_bf16_f32 v40, v42, v43
	v_cvt_pk_bf16_f32 v41, v68, v71
	s_nop 1
	s_waitcnt lgkmcnt(3)
	v_mfma_f32_16x16x32_bf16 v[8:11], v[72:75], v[38:41], v[8:11]
	s_waitcnt lgkmcnt(2)
	v_mfma_f32_16x16x32_bf16 v[12:15], v[186:189], v[38:41], v[12:15]
	s_waitcnt lgkmcnt(1)
	v_mfma_f32_16x16x32_bf16 v[4:7], v[190:193], v[38:41], v[4:7]
	s_waitcnt lgkmcnt(0)
	v_mfma_f32_16x16x32_bf16 v[0:3], v[194:197], v[38:41], v[0:3]
	s_and_b64 vcc, exec, s[10:11]
	s_cbranch_vccnz .LBB0_544
	s_branch .LBB0_574

; #define LAS __attribute__((address_space(3)))
; __device__ __forceinline__ f32x4 mfma16(const bf16x8& a, const bf16x8& b, const f32x4& c) { return __builtin_amdgcn_mfma_f32_16x16x32_bf16(a, b, c, 0, 0, 0); }
; __device__ __forceinline__ void attn_items(const Params& p, LAS unsigned char* lds, int ai0, int aistride) {
;     ...
;                 for (int u = 0; u < 6; ++u) {
;                     if (2 * u < nkt) {
;                         const bf16x8 Pf = pack8(s[2 * u], s[2 * u + 1]);
; #pragma unroll
;                         for (int dt = 0; dt < 4; ++dt) {
;                             const u32x2 lo = *(const LAS u32x2*)(Vt_s + (16 * dt + fr) * 200 + 32 * u + 4 * fq), hi = *(const LAS u32x2*)(Vt_s + (16 * dt + fr) * 200 + 32 * u + 16 + 4 * fq);
;                             o[dt] = mfma16(cat8(lo, hi), Pf, o[dt]);
;                         }
.LBB0_572:
	v_cvt_pk_bf16_f32 v89, v72, v73
	v_cvt_pk_bf16_f32 v90, v74, v75
	ds_read2_b64 v[72:75], v65 offset0:184 offset1:188
	ds_read2_b64 v[186:189], v67 offset0:152 offset1:156
	ds_read2_b64 v[190:193], v69 offset0:216 offset1:220
	ds_read2_b64 v[194:197], v82 offset0:248 offset1:252
	v_cvt_pk_bf16_f32 v88, v66, v70
	v_cvt_pk_bf16_f32 v91, v77, v79
	s_nop 1
	s_waitcnt lgkmcnt(3)
	v_mfma_f32_16x16x32_bf16 v[12:15], v[72:75], v[88:91], v[12:15]
	s_waitcnt lgkmcnt(2)
	v_mfma_f32_16x16x32_bf16 v[8:11], v[186:189], v[88:91], v[8:11]
	s_waitcnt lgkmcnt(1)
	v_mfma_f32_16x16x32_bf16 v[4:7], v[190:193], v[88:91], v[4:7]
	s_waitcnt lgkmcnt(0)
	v_mfma_f32_16x16x32_bf16 v[0:3], v[194:197], v[88:91], v[0:3]
	s_and_b64 vcc, exec, s[8:9]
	v_add_u32_e32 v16, 0xb800, v50
	s_cbranch_vccz .LBB0_570

; #define LAS __attribute__((address_space(3)))
; __device__ __forceinline__ f32x4 mfma16(const bf16x8& a, const bf16x8& b, const f32x4& c) { return __builtin_amdgcn_mfma_f32_16x16x32_bf16(a, b, c, 0, 0, 0); }
; __device__ __forceinline__ void attn_items(const Params& p, LAS unsigned char* lds, int ai0, int aistride) {
;     ...
;                 for (int u = 0; u < 6; ++u) {
;                     if (2 * u < nkt) {
;                         const bf16x8 Pf = pack8(s[2 * u], s[2 * u + 1]);
; #pragma unroll
;                         for (int dt = 0; dt < 4; ++dt) {
;                             const u32x2 lo = *(const LAS u32x2*)(Vt_s + (16 * dt + fr) * 200 + 32 * u + 4 * fq), hi = *(const LAS u32x2*)(Vt_s + (16 * dt + fr) * 200 + 32 * u + 16 + 4 * fq);
;                             o[dt] = mfma16(cat8(lo, hi), Pf, o[dt]);
;                         }
.LBB0_574:
	ds_read2_b64 v[38:41], v67 offset0:168 offset1:172
	ds_read2_b64 v[186:189], v65 offset0:200 offset1:204
	ds_read2_b64 v[190:193], v69 offset0:232 offset1:236
	ds_read2_b64 v[194:197], v16 offset0:8 offset1:12
	v_cvt_pk_bf16_f32 v32, v32, v33
	v_cvt_pk_bf16_f32 v33, v34, v35
	v_cvt_pk_bf16_f32 v34, v36, v37
	v_cvt_pk_bf16_f32 v35, v80, v81
	s_nop 1
	s_waitcnt lgkmcnt(3)
	v_mfma_f32_16x16x32_bf16 v[8:11], v[38:41], v[32:35], v[8:11]
	s_waitcnt lgkmcnt(2)
	v_mfma_f32_16x16x32_bf16 v[12:15], v[186:189], v[32:35], v[12:15]
	s_waitcnt lgkmcnt(1)
	v_mfma_f32_16x16x32_bf16 v[4:7], v[190:193], v[32:35], v[4:7]
	s_waitcnt lgkmcnt(0)
	v_mfma_f32_16x16x32_bf16 v[0:3], v[194:197], v[32:35], v[0:3]
	s_branch .LBB0_544

; #define SC_BAR() do { asm volatile("s_waitcnt lgkmcnt(0)" ::: "memory"); __builtin_amdgcn_s_barrier(); asm volatile("" ::: "memory"); } while (0)
; #define SC_UG(chs) do { const bf16_t* U_ = (const bf16_t*)(p.ws + WS_UT) + (size_t)(chs) * 8192; const float* G_ = (const float*)(p.ws + WS_GB) + (size_t)(chs) * 64; \
;         _Pragma("unroll") for (int tt = 0; tt < 4; ++tt) { u4n[tt] = *(const bf16x4*)(U_ + dv * 64 + 16 * tt + 4 * fq); g4n[tt] = *(const f32x4*)(G_ + 16 * tt + 4 * fq); } \
;         Gln = G_[63]; } while (0)
; template <bool PROMPT>
; __device__ __forceinline__ void scan_block(const Params& p, LAS unsigned char* lds, int chs0, int nsteps, const float* s0, float* sfin, int rowbase, int ntok, int h, int half) {
;     ...
;     bf16_t* CAT = (bf16_t*)(p.ws + WS_CAT);
;     f32x4 ST[8];
; #pragma unroll
;     for (int T = 0; T < 8; ++T)
; #pragma unroll
;         for (int jj = 0; jj < 4; ++jj) ST[T][jj] = s0 ? s0[(size_t)(16 * T + 4 * fq + jj) * 128 + dv] : 0.f;
;     bf16x4 u4n[4]; f32x4 g4n[4]; float Gln;
;     ...
;     SC_UG(chs0);
;     SC_BAR();
.LBB0_600:
	s_andn2_saveexec_b64 s[2:3], s[2:3]
	s_cbranch_execz .LBB0_604
	s_lshl_b32 s1, s33, 6
	s_mov_b32 s5, 0
	s_and_b32 s1, s1, 64
	s_waitcnt vmcnt(0)
	v_lshrrev_b32_e32 v0, 2, v184
	s_lshl_b64 s[6:7], s[4:5], 14
	v_and_b32_e32 v0, 48, v0
	s_add_u32 s10, s50, s6
	v_or3_b32 v160, s1, v0, v128
	s_addc_u32 s11, s51, s7
	s_lshl_b64 s[8:9], s[4:5], 8
	v_bfe_u32 v162, v184, 4, 2
	s_add_u32 s1, s50, s8
	v_mov_b32_e32 v121, 0
	v_lshlrev_b32_e32 v120, 7, v160
	s_addc_u32 s4, s51, s9
	v_lshl_add_u64 v[0:1], s[10:11], 0, v[120:121]
	v_lshlrev_b32_e32 v16, 3, v162
	v_mov_b32_e32 v17, v121
	s_add_u32 s14, s1, 0xd0e8800
	v_lshl_add_u64 v[0:1], v[0:1], 0, v[16:17]
	s_mov_b32 s1, 0xbee8000
	s_addc_u32 s15, s4, 0
	s_mov_b64 s[10:11], 0xbee8800
	v_add_co_u32_e32 v20, vcc, s1, v0
	v_lshlrev_b32_e32 v163, 4, v162
	v_lshl_add_u64 v[18:19], v[0:1], 0, s[10:11]
	v_addc_co_u32_e32 v21, vcc, 0, v1, vcc
	global_load_dwordx4 v[12:15], v163, s[14:15]
	global_load_dwordx4 v[8:11], v163, s[14:15] offset:64
	global_load_dwordx2 v[118:119], v[20:21], off offset:2048
	global_load_dwordx2 v[116:117], v[18:19], off offset:32
	global_load_dwordx2 v[114:115], v[18:19], off offset:64
	global_load_dwordx2 v[112:113], v[18:19], off offset:96
	global_load_dwordx4 v[4:7], v163, s[14:15] offset:128
	global_load_dwordx4 v[0:3], v163, s[14:15] offset:192
	global_load_dword v165, v121, s[14:15] offset:252
	s_movk_i32 s4, 0x110
	v_mov_b32_e32 v17, 0x1100
	v_mad_u32_u24 v168, v128, s4, v17
	v_mov_b32_e32 v17, 0x2200
	v_mad_u32_u24 v167, v128, s4, v17
	v_mov_b32_e32 v17, 0x3300
	v_mad_u32_u24 v166, v128, s4, v17
	s_lshl_b32 s4, s33, 18
	s_lshl_b32 s1, s0, 7
	s_and_b32 s4, s4, 0xe00000
	s_and_b32 s1, s1, 0x180
	v_lshl_or_b32 v17, v162, 12, s4
	v_or3_b32 v17, v17, s1, v160
	v_lshlrev_b32_e32 v17, 1, v17
	v_or_b32_e32 v18, 0x19c00, v17
	v_mov_b32_e32 v19, v121
	s_mov_b64 s[10:11], 0x9b40000
	v_lshl_add_u64 v[122:123], v[18:19], 0, s[10:11]
	v_or_b32_e32 v18, 0x19400, v17
	v_lshl_add_u64 v[124:125], v[18:19], 0, s[10:11]
	v_or_b32_e32 v18, 0x18c00, v17
	v_lshl_add_u64 v[126:127], v[18:19], 0, s[10:11]
	v_or_b32_e32 v18, 0x18400, v17
	v_mul_u32_u24_e32 v169, 0x110, v128
	v_mul_u32_u24_e32 v164, 0x90, v128
	v_lshl_add_u64 v[128:129], v[18:19], 0, s[10:11]
	v_or_b32_e32 v18, 0x11c00, v17
	v_lshl_add_u64 v[130:131], v[18:19], 0, s[10:11]
	v_or_b32_e32 v18, 0x11400, v17
	v_lshl_add_u64 v[132:133], v[18:19], 0, s[10:11]
	v_or_b32_e32 v18, 0x10c00, v17
	v_lshl_add_u64 v[134:135], v[18:19], 0, s[10:11]
	v_or_b32_e32 v18, 0x10400, v17
	v_lshl_add_u64 v[136:137], v[18:19], 0, s[10:11]
	v_or_b32_e32 v18, 0x9c00, v17
	v_lshl_add_u64 v[138:139], v[18:19], 0, s[10:11]
	v_or_b32_e32 v18, 0x9400, v17
	v_lshl_add_u64 v[140:141], v[18:19], 0, s[10:11]
	v_or_b32_e32 v18, 0x8c00, v17
	v_lshl_add_u64 v[142:143], v[18:19], 0, s[10:11]
	v_or_b32_e32 v18, 0x8400, v17
	v_lshl_add_u64 v[144:145], v[18:19], 0, s[10:11]
	v_or_b32_e32 v18, 0x1c00, v17
	v_lshl_add_u64 v[146:147], v[18:19], 0, s[10:11]
	v_or_b32_e32 v18, 0x1400, v17
	s_waitcnt lgkmcnt(0)
	s_barrier
	v_lshl_add_u64 v[148:149], v[18:19], 0, s[10:11]
	v_or_b32_e32 v18, 0xc00, v17
	v_lshl_add_u64 v[150:151], v[18:19], 0, s[10:11]
	v_or_b32_e32 v18, 0x400, v17
	s_add_u32 s4, s8, 0xd0e89fc
	v_or3_b32 v16, s6, v120, v16
	v_mov_b32_e32 v17, s7
	s_mov_b64 s[6:7], 0xbeec840
	v_lshrrev_b32_e32 v161, 4, v184
	v_lshlrev_b32_e32 v170, 2, v162
	v_lshl_add_u64 v[152:153], v[18:19], 0, s[10:11]
	v_or_b32_e32 v154, s8, v163
	v_mov_b32_e32 v155, s9
	s_addc_u32 s14, s9, 0
	v_lshl_add_u64 v[156:157], v[16:17], 0, s[6:7]
	s_mov_b32 s15, 0xd0e8000
	s_mov_b64 s[6:7], 0x20000
	s_mov_b64 s[8:9], 0x100
	s_mov_b64 s[10:11], 0x4000
	v_mov_b32_e32 v32, 0
	v_mov_b32_e32 v33, v121
	v_mov_b32_e32 v34, v121
	v_mov_b32_e32 v35, v121
	v_mov_b32_e32 v36, 0
	v_mov_b32_e32 v37, v121
	v_mov_b32_e32 v38, v121
	v_mov_b32_e32 v39, v121
	v_mov_b32_e32 v40, 0
	v_mov_b32_e32 v41, v121
	v_mov_b32_e32 v42, v121
	v_mov_b32_e32 v43, v121
	v_mov_b32_e32 v44, 0
	v_mov_b32_e32 v45, v121
	v_mov_b32_e32 v46, v121
	v_mov_b32_e32 v47, v121
	v_mov_b32_e32 v16, 0
	v_mov_b32_e32 v17, v121
	v_mov_b32_e32 v18, v121
	v_mov_b32_e32 v20, 0
	v_mov_b32_e32 v21, v121
	v_mov_b32_e32 v22, v121
	v_mov_b32_e32 v23, v121
	v_mov_b32_e32 v24, 0
	v_mov_b32_e32 v25, v121
	v_mov_b32_e32 v26, v121
	v_mov_b32_e32 v27, v121
	v_mov_b32_e32 v28, 0
	v_mov_b32_e32 v29, v121
	v_mov_b32_e32 v30, v121
	v_mov_b32_e32 v31, v121
	s_waitcnt vmcnt(0)
	s_mov_b64 s[96:97], s[50:51]
	s_branch .Lsc_body

; #define LAS __attribute__((address_space(3)))
; __device__ __forceinline__ f32x4 mfma16(const bf16x8& a, const bf16x8& b, const f32x4& c) { return __builtin_amdgcn_mfma_f32_16x16x32_bf16(a, b, c, 0, 0, 0); }
; #define SC_UG(chs) do { const bf16_t* U_ = (const bf16_t*)(p.ws + WS_UT) + (size_t)(chs) * 8192; const float* G_ = (const float*)(p.ws + WS_GB) + (size_t)(chs) * 64; \
;         _Pragma("unroll") for (int tt = 0; tt < 4; ++tt) { u4n[tt] = *(const bf16x4*)(U_ + dv * 64 + 16 * tt + 4 * fq); g4n[tt] = *(const f32x4*)(G_ + 16 * tt + 4 * fq); } \
;         Gln = G_[63]; } while (0)
; template <bool PROMPT>
; __device__ __forceinline__ void scan_block(const Params& p, LAS unsigned char* lds, int chs0, int nsteps, const float* s0, float* sfin, int rowbase, int ntok, int h, int half) {
;     ...
;     for (int n = 0; n < nsteps; ++n) {
;         bf16x4 u4[4]; f32x4 g4[4]; const float Glc = Gln;
; #pragma unroll
;         for (int tt = 0; tt < 4; ++tt) { u4[tt] = u4n[tt]; g4[tt] = g4n[tt]; }
;         if constexpr (PROMPT) { const int c = (n + 1 < nsteps) ? n + 1 : nsteps - 1; SC_UG(chs0 + c); }
;         __builtin_amdgcn_sched_barrier(0);
;         const LAS unsigned char* B = lds + (n & 1) * SC_BUF;
;         bf16x8 Sb[4];
; #pragma unroll
;         for (int P = 0; P < 4; ++P) Sb[P] = pack8(ST[2 * P], ST[2 * P + 1]);
;         f32x4 ws[4], qs[4];
;         bf16x8 fa[8];
; #pragma unroll
;         for (int tt = 0; tt < 4; ++tt) {
; #pragma unroll
;             for (int P = 0; P < 4; ++P) { fa[P] = *(const LAS bf16x8*)(B + SC_W + (16 * tt + fr) * 272 + (32 * P + 8 * fq) * 2);
;                                           fa[4 + P] = *(const LAS bf16x8*)(B + SC_QS + (16 * tt + fr) * 272 + (32 * P + 8 * fq) * 2); }
;             __builtin_amdgcn_sched_barrier(0);
;             ws[tt] = (f32x4){0.f, 0.f, 0.f, 0.f}; qs[tt] = (f32x4){0.f, 0.f, 0.f, 0.f};
; #pragma unroll
;             for (int P = 0; P < 4; ++P) { ws[tt] = mfma16(fa[P], Sb[P], ws[tt]); qs[tt] = mfma16(fa[4 + P], Sb[P], qs[tt]); }
;             __builtin_amdgcn_sched_barrier(0);
;         }
.Lsc_body:
	v_mov_b64_e32 v[50:51], v[2:3]
	v_mov_b64_e32 v[48:49], v[0:1]
	v_lshl_add_u64 v[2:3], s[50:51], 0, v[154:155]
	v_add_co_u32_e32 v2, vcc, s15, v2
	v_mov_b64_e32 v[62:63], v[14:15]
	v_mov_b64_e32 v[58:59], v[10:11]
	v_mov_b64_e32 v[54:55], v[6:7]
	s_add_i32 s16, s5, 1
	v_lshl_add_u64 v[0:1], s[50:51], 0, v[156:157]
	v_addc_co_u32_e32 v3, vcc, 0, v3, vcc
	v_mov_b64_e32 v[60:61], v[12:13]
	v_mov_b64_e32 v[56:57], v[8:9]
	v_mov_b64_e32 v[52:53], v[4:5]
	v_mov_b64_e32 v[202:203], v[118:119]
	v_mov_b64_e32 v[158:159], v[116:117]
	v_mov_b64_e32 v[66:67], v[114:115]
	v_mov_b64_e32 v[64:65], v[112:113]
	global_load_dwordx2 v[118:119], v[0:1], off offset:-64
	global_load_dwordx2 v[116:117], v[0:1], off offset:-32
	global_load_dwordx2 v[114:115], v[0:1], off
	global_load_dwordx2 v[112:113], v[0:1], off offset:32
	s_add_u32 s18, s50, s4
	global_load_dwordx4 v[12:15], v[2:3], off offset:2304
	global_load_dwordx4 v[8:11], v[2:3], off offset:2368
	global_load_dwordx4 v[4:7], v[2:3], off offset:2432
	s_nop 0
	global_load_dwordx4 v[0:3], v[2:3], off offset:2496
	s_addc_u32 s19, s51, s14
	v_mov_b32_e32 v120, v165
	global_load_dword v165, v121, s[18:19]
	s_bitcmp1_b32 s5, 0
	s_cselect_b32 s5, 0xf400, 0
	s_add_i32 s5, s5, 0
	v_add_u32_e32 v171, s5, v163
	v_add_u32_e32 v108, v171, v169
	ds_read_b128 v[80:83], v108
	ds_read_b128 v[84:87], v108 offset:64
	ds_read_b128 v[88:91], v108 offset:17408
	ds_read_b128 v[92:95], v108 offset:17472
	ds_read_b128 v[96:99], v108 offset:128
	ds_read_b128 v[100:103], v108 offset:192
	ds_read_b128 v[104:107], v108 offset:17536
	ds_read_b128 v[108:111], v108 offset:17600
	v_cvt_pk_bf16_f32 v68, v28, v29
	v_cvt_pk_bf16_f32 v69, v30, v31
	v_cvt_pk_bf16_f32 v70, v24, v25
	v_cvt_pk_bf16_f32 v71, v26, v27
	v_cvt_pk_bf16_f32 v72, v20, v21
	v_cvt_pk_bf16_f32 v73, v22, v23
	v_cvt_pk_bf16_f32 v74, v16, v17
	v_cvt_pk_bf16_f32 v75, v18, v19
	v_cvt_pk_bf16_f32 v76, v44, v45
	v_cvt_pk_bf16_f32 v77, v46, v47
	v_cvt_pk_bf16_f32 v78, v40, v41
	v_cvt_pk_bf16_f32 v79, v42, v43
	v_cvt_pk_bf16_f32 v172, v36, v37
	v_cvt_pk_bf16_f32 v173, v38, v39
	v_cvt_pk_bf16_f32 v174, v32, v33
	v_cvt_pk_bf16_f32 v175, v34, v35
	s_waitcnt lgkmcnt(0)
	v_mfma_f32_16x16x32_bf16 v[80:83], v[80:83], v[68:71], 0
	v_mfma_f32_16x16x32_bf16 v[88:91], v[88:91], v[68:71], 0
	v_mfma_f32_16x16x32_bf16 v[80:83], v[84:87], v[72:75], v[80:83]
	v_mfma_f32_16x16x32_bf16 v[84:87], v[92:95], v[72:75], v[88:91]
	v_mfma_f32_16x16x32_bf16 v[80:83], v[96:99], v[76:79], v[80:83]
	v_mfma_f32_16x16x32_bf16 v[84:87], v[104:107], v[76:79], v[84:87]
	v_mfma_f32_16x16x32_bf16 v[176:179], v[100:103], v[172:175], v[80:83]
	v_mfma_f32_16x16x32_bf16 v[104:107], v[108:111], v[172:175], v[84:87]
	v_add_u32_e32 v180, v171, v168
	s_nop 3
	ds_read_b128 v[80:83], v180
	ds_read_b128 v[84:87], v180 offset:64
	ds_read_b128 v[88:91], v180 offset:17408
	ds_read_b128 v[92:95], v180 offset:17472
	ds_read_b128 v[96:99], v180 offset:128
	ds_read_b128 v[100:103], v180 offset:192
	ds_read_b128 v[108:111], v180 offset:17536
	ds_read_b128 v[180:183], v180 offset:17600
	s_waitcnt lgkmcnt(7)
	v_mfma_f32_16x16x32_bf16 v[80:83], v[80:83], v[68:71], 0
	s_waitcnt lgkmcnt(5)
	v_mfma_f32_16x16x32_bf16 v[88:91], v[88:91], v[68:71], 0
	v_mfma_f32_16x16x32_bf16 v[80:83], v[84:87], v[72:75], v[80:83]
	s_waitcnt lgkmcnt(4)
	v_mfma_f32_16x16x32_bf16 v[84:87], v[92:95], v[72:75], v[88:91]
	s_waitcnt lgkmcnt(3)
	v_mfma_f32_16x16x32_bf16 v[80:83], v[96:99], v[76:79], v[80:83]
	s_waitcnt lgkmcnt(1)
	v_mfma_f32_16x16x32_bf16 v[84:87], v[108:111], v[76:79], v[84:87]
	v_mfma_f32_16x16x32_bf16 v[186:189], v[100:103], v[172:175], v[80:83]
	s_waitcnt lgkmcnt(0)
	v_mfma_f32_16x16x32_bf16 v[180:183], v[180:183], v[172:175], v[84:87]
	v_add_u32_e32 v185, v171, v167
	s_nop 1
	ds_read_b128 v[80:83], v185
	s_nop 0
	ds_read_b128 v[84:87], v185 offset:64
	ds_read_b128 v[88:91], v185 offset:17408
	ds_read_b128 v[92:95], v185 offset:17472
	ds_read_b128 v[96:99], v185 offset:128
	ds_read_b128 v[100:103], v185 offset:192
	ds_read_b128 v[108:111], v185 offset:17536
	ds_read_b128 v[190:193], v185 offset:17600
	s_waitcnt lgkmcnt(7)
	v_mfma_f32_16x16x32_bf16 v[80:83], v[80:83], v[68:71], 0
	s_waitcnt lgkmcnt(5)
	v_mfma_f32_16x16x32_bf16 v[88:91], v[88:91], v[68:71], 0
	v_mfma_f32_16x16x32_bf16 v[80:83], v[84:87], v[72:75], v[80:83]
	s_waitcnt lgkmcnt(4)
	v_mfma_f32_16x16x32_bf16 v[84:87], v[92:95], v[72:75], v[88:91]
	s_waitcnt lgkmcnt(3)
	v_mfma_f32_16x16x32_bf16 v[80:83], v[96:99], v[76:79], v[80:83]
	s_waitcnt lgkmcnt(1)
	v_mfma_f32_16x16x32_bf16 v[84:87], v[108:111], v[76:79], v[84:87]
	v_mfma_f32_16x16x32_bf16 v[194:197], v[100:103], v[172:175], v[80:83]
	s_waitcnt lgkmcnt(0)
	v_mfma_f32_16x16x32_bf16 v[100:103], v[190:193], v[172:175], v[84:87]
	v_add_u32_e32 v185, v171, v166
	s_nop 1
	ds_read_b128 v[80:83], v185
	s_nop 0
	ds_read_b128 v[84:87], v185 offset:64
	ds_read_b128 v[88:91], v185 offset:17408
	ds_read_b128 v[92:95], v185 offset:17472
	ds_read_b128 v[96:99], v185 offset:128
	ds_read_b128 v[108:111], v185 offset:192
	ds_read_b128 v[190:193], v185 offset:17536
	ds_read_b128 v[198:201], v185 offset:17600
	s_waitcnt lgkmcnt(7)
	v_mfma_f32_16x16x32_bf16 v[80:83], v[80:83], v[68:71], 0
	s_waitcnt lgkmcnt(5)
	v_mfma_f32_16x16x32_bf16 v[68:71], v[88:91], v[68:71], 0
	v_mfma_f32_16x16x32_bf16 v[80:83], v[84:87], v[72:75], v[80:83]
	s_waitcnt lgkmcnt(4)
	v_mfma_f32_16x16x32_bf16 v[68:71], v[92:95], v[72:75], v[68:71]
	s_waitcnt lgkmcnt(3)
	v_mfma_f32_16x16x32_bf16 v[72:75], v[96:99], v[76:79], v[80:83]
	s_waitcnt lgkmcnt(1)
	v_mfma_f32_16x16x32_bf16 v[68:71], v[190:193], v[76:79], v[68:71]
	v_mfma_f32_16x16x32_bf16 v[190:193], v[108:111], v[172:175], v[72:75]
	s_waitcnt lgkmcnt(0)
; #define LAS __attribute__((address_space(3)))
; __device__ __forceinline__ float bf2f(short b) { return __uint_as_float(((unsigned)(unsigned short)b) << 16); }
; template <bool PROMPT>
; __device__ __forceinline__ void scan_block(const Params& p, LAS unsigned char* lds, int chs0, int nsteps, const float* s0, float* sfin, int rowbase, int ntok, int h, int half) {
;     ...
;         bf16x8 fq_[8], fk[8];
; #pragma unroll
;         for (int tt = 0; tt < 4; ++tt)
; #pragma unroll
;             for (int u = 0; u < 2; ++u) fq_[tt * 2 + u] = *(const LAS bf16x8*)(B + SC_QK + (16 * tt + fr) * 144 + (32 * u + 8 * fq) * 2);
;         __builtin_amdgcn_sched_barrier(0);
;         f32x4 vn[4], vd[4];
; #pragma unroll
;         for (int tt = 0; tt < 4; ++tt)
; #pragma unroll
;             for (int jj = 0; jj < 4; ++jj) { vn[tt][jj] = bf2f(u4[tt][jj]) - ws[tt][jj]; vd[tt][jj] = vn[tt][jj] * __expf(Glc - g4[tt][jj]); }
;         bf16x8 Vb[2], Vd[2];
; #pragma unroll
;         for (int u = 0; u < 2; ++u) { Vb[u] = pack8(vn[2 * u], vn[2 * u + 1]); Vd[u] = pack8(vd[2 * u], vd[2 * u + 1]); }
;         f32x4 o[4];
; #pragma unroll
;         for (int tt = 0; tt < 4; ++tt)
; #pragma unroll
;             for (int jj = 0; jj < 4; ++jj) o[tt][jj] = qs[tt][jj] * __expf(g4[tt][jj]);
;         const float gt = __expf(Glc);
; #pragma unroll
;         for (int T = 0; T < 8; ++T) ST[T] = ST[T] * gt;
;         __builtin_amdgcn_sched_barrier(0);
; #pragma unroll
;         for (int T = 0; T < 4; ++T)
; #pragma unroll
;             for (int u = 0; u < 2; ++u) fk[T * 2 + u] = *(const LAS bf16x8*)(B + SC_KT + (16 * T + fr) * 144 + (32 * u + 8 * fq) * 2);
	v_mfma_f32_16x16x32_bf16 v[108:111], v[198:201], v[172:175], v[68:71]
	v_add_u32_e32 v171, v171, v164
	s_nop 3
	ds_read_b128 v[68:71], v171 offset:53248
	ds_read_b128 v[72:75], v171 offset:53312
	ds_read_b128 v[76:79], v171 offset:55552
	ds_read_b128 v[80:83], v171 offset:55616
	ds_read_b128 v[84:87], v171 offset:57856
	ds_read_b128 v[88:91], v171 offset:57920
	ds_read_b128 v[92:95], v171 offset:60160
	ds_read_b128 v[96:99], v171 offset:60224
	v_sub_f32_e32 v172, v120, v60
	v_sub_f32_e32 v173, v120, v61
	v_mul_f32_e32 v172, 0x3fb8aa3b, v172
	v_mul_f32_e32 v173, 0x3fb8aa3b, v173
	v_exp_f32_e32 v172, v172
	v_exp_f32_e32 v173, v173
	v_and_b32_e32 v175, 0xffff0000, v202
	v_lshlrev_b32_e32 v174, 16, v202
	v_pk_add_f32 v[174:175], v[174:175], v[176:177] neg_lo:[0,1] neg_hi:[0,1]
	v_and_b32_e32 v199, 0xffff0000, v203
	v_pk_mul_f32 v[176:177], v[172:173], v[174:175]
	v_sub_f32_e32 v172, v120, v62
	v_sub_f32_e32 v173, v120, v63
	v_mul_f32_e32 v172, 0x3fb8aa3b, v172
	v_mul_f32_e32 v173, 0x3fb8aa3b, v173
	v_exp_f32_e32 v172, v172
	v_exp_f32_e32 v173, v173
	v_lshlrev_b32_e32 v198, 16, v203
	v_pk_add_f32 v[178:179], v[198:199], v[178:179] neg_lo:[0,1] neg_hi:[0,1]
	v_and_b32_e32 v201, 0xffff0000, v158
	v_pk_mul_f32 v[198:199], v[172:173], v[178:179]
	v_sub_f32_e32 v172, v120, v56
	v_sub_f32_e32 v173, v120, v57
	v_mul_f32_e32 v172, 0x3fb8aa3b, v172
	v_mul_f32_e32 v173, 0x3fb8aa3b, v173
	v_exp_f32_e32 v172, v172
	v_exp_f32_e32 v173, v173
	v_lshlrev_b32_e32 v200, 16, v158
	v_sub_f32_e32 v158, v120, v58
	v_pk_add_f32 v[186:187], v[200:201], v[186:187] neg_lo:[0,1] neg_hi:[0,1]
	v_mul_f32_e32 v158, 0x3fb8aa3b, v158
	v_pk_mul_f32 v[200:201], v[172:173], v[186:187]
	v_exp_f32_e32 v172, v158
	v_sub_f32_e32 v158, v120, v59
	v_mul_f32_e32 v158, 0x3fb8aa3b, v158
	v_exp_f32_e32 v173, v158
	v_and_b32_e32 v203, 0xffff0000, v159
	v_lshlrev_b32_e32 v202, 16, v159
	v_pk_add_f32 v[158:159], v[202:203], v[188:189] neg_lo:[0,1] neg_hi:[0,1]
	v_and_b32_e32 v203, 0xffff0000, v66
	v_pk_mul_f32 v[188:189], v[172:173], v[158:159]
	v_sub_f32_e32 v172, v120, v52
	v_sub_f32_e32 v173, v120, v53
	v_mul_f32_e32 v172, 0x3fb8aa3b, v172
	v_mul_f32_e32 v173, 0x3fb8aa3b, v173
	v_exp_f32_e32 v172, v172
	v_exp_f32_e32 v173, v173
	v_lshlrev_b32_e32 v202, 16, v66
	v_sub_f32_e32 v66, v120, v54
	v_pk_add_f32 v[194:195], v[202:203], v[194:195] neg_lo:[0,1] neg_hi:[0,1]
	v_mul_f32_e32 v66, 0x3fb8aa3b, v66
	v_pk_mul_f32 v[202:203], v[172:173], v[194:195]
	v_exp_f32_e32 v172, v66
	v_sub_f32_e32 v66, v120, v55
	v_mul_f32_e32 v66, 0x3fb8aa3b, v66
	v_exp_f32_e32 v173, v66
	v_and_b32_e32 v205, 0xffff0000, v67
	v_lshlrev_b32_e32 v204, 16, v67
	v_pk_add_f32 v[66:67], v[204:205], v[196:197] neg_lo:[0,1] neg_hi:[0,1]
	v_and_b32_e32 v205, 0xffff0000, v64
	v_pk_mul_f32 v[196:197], v[172:173], v[66:67]
	v_sub_f32_e32 v172, v120, v48
	v_sub_f32_e32 v173, v120, v49
	v_mul_f32_e32 v172, 0x3fb8aa3b, v172
	v_mul_f32_e32 v173, 0x3fb8aa3b, v173
	v_exp_f32_e32 v172, v172
	v_exp_f32_e32 v173, v173
	v_lshlrev_b32_e32 v204, 16, v64
	v_sub_f32_e32 v64, v120, v50
	v_pk_add_f32 v[190:191], v[204:205], v[190:191] neg_lo:[0,1] neg_hi:[0,1]
	v_mul_f32_e32 v64, 0x3fb8aa3b, v64
	v_pk_mul_f32 v[204:205], v[172:173], v[190:191]
	v_exp_f32_e32 v172, v64
	v_sub_f32_e32 v64, v120, v51
	v_mul_f32_e32 v64, 0x3fb8aa3b, v64
	v_exp_f32_e32 v173, v64
	v_mul_f32_e32 v60, 0x3fb8aa3b, v60
	v_mul_f32_e32 v61, 0x3fb8aa3b, v61
	v_and_b32_e32 v207, 0xffff0000, v65
	v_lshlrev_b32_e32 v206, 16, v65
	v_exp_f32_e32 v60, v60
	v_exp_f32_e32 v61, v61
	v_mul_f32_e32 v54, 0x3fb8aa3b, v54
	v_mul_f32_e32 v55, 0x3fb8aa3b, v55
	v_pk_add_f32 v[64:65], v[206:207], v[192:193] neg_lo:[0,1] neg_hi:[0,1]
	v_mul_f32_e32 v56, 0x3fb8aa3b, v56
	v_exp_f32_e32 v54, v54
	v_exp_f32_e32 v55, v55
	v_pk_mul_f32 v[192:193], v[172:173], v[64:65]
	v_cvt_pk_bf16_f32 v172, v174, v175
	v_cvt_pk_bf16_f32 v175, v158, v159
	v_mul_f32_e32 v62, 0x3fb8aa3b, v62
	v_mul_f32_e32 v63, 0x3fb8aa3b, v63
	v_exp_f32_e32 v158, v56
	v_mul_f32_e32 v56, 0x3fb8aa3b, v57
	v_mul_f32_e32 v57, 0x3fb8aa3b, v58
	v_cvt_pk_bf16_f32 v173, v178, v179
	v_cvt_pk_bf16_f32 v179, v188, v189
	v_cvt_pk_bf16_f32 v188, v190, v191
	v_exp_f32_e32 v62, v62
	v_exp_f32_e32 v63, v63
	v_exp_f32_e32 v190, v57
	v_mul_f32_e32 v57, 0x3fb8aa3b, v59
	v_mul_f32_e32 v52, 0x3fb8aa3b, v52
	v_exp_f32_e32 v191, v57
	v_exp_f32_e32 v159, v56
	v_pk_mul_f32 v[56:57], v[60:61], v[104:105]
	v_exp_f32_e32 v104, v52
	v_mul_f32_e32 v52, 0x3fb8aa3b, v53
	v_mul_f32_e32 v50, 0x3fb8aa3b, v50
	v_exp_f32_e32 v105, v52
	v_pk_mul_f32 v[52:53], v[54:55], v[102:103]
	v_exp_f32_e32 v54, v50
	v_mul_f32_e32 v50, 0x3fb8aa3b, v51
	v_exp_f32_e32 v55, v50
	v_mul_f32_e32 v50, 0x3fb8aa3b, v120
	v_pk_mul_f32 v[58:59], v[62:63], v[106:107]
	v_mul_f32_e32 v48, 0x3fb8aa3b, v48
	v_mul_f32_e32 v49, 0x3fb8aa3b, v49
	v_exp_f32_e32 v106, v50
	v_exp_f32_e32 v48, v48
	v_exp_f32_e32 v49, v49
	v_cvt_pk_bf16_f32 v174, v186, v187
	v_pk_mul_f32 v[30:31], v[30:31], v[106:107] op_sel_hi:[1,0]
	v_pk_mul_f32 v[28:29], v[28:29], v[106:107] op_sel_hi:[1,0]
	v_pk_mul_f32 v[26:27], v[26:27], v[106:107] op_sel_hi:[1,0]
	v_pk_mul_f32 v[24:25], v[24:25], v[106:107] op_sel_hi:[1,0]
	v_pk_mul_f32 v[22:23], v[22:23], v[106:107] op_sel_hi:[1,0]
	v_pk_mul_f32 v[20:21], v[20:21], v[106:107] op_sel_hi:[1,0]
	v_pk_mul_f32 v[18:19], v[18:19], v[106:107] op_sel_hi:[1,0]
	v_pk_mul_f32 v[16:17], v[16:17], v[106:107] op_sel_hi:[1,0]
	v_pk_mul_f32 v[46:47], v[46:47], v[106:107] op_sel_hi:[1,0]
	v_pk_mul_f32 v[44:45], v[44:45], v[106:107] op_sel_hi:[1,0]
	v_pk_mul_f32 v[42:43], v[42:43], v[106:107] op_sel_hi:[1,0]
	v_pk_mul_f32 v[40:41], v[40:41], v[106:107] op_sel_hi:[1,0]
	v_pk_mul_f32 v[38:39], v[38:39], v[106:107] op_sel_hi:[1,0]
	v_pk_mul_f32 v[36:37], v[36:37], v[106:107] op_sel_hi:[1,0]
	v_pk_mul_f32 v[34:35], v[34:35], v[106:107] op_sel_hi:[1,0]
	v_pk_mul_f32 v[32:33], v[32:33], v[106:107] op_sel_hi:[1,0]
	v_cvt_pk_bf16_f32 v176, v176, v177
	v_cvt_pk_bf16_f32 v177, v198, v199
	v_cvt_pk_bf16_f32 v178, v200, v201
	v_cvt_pk_bf16_f32 v186, v194, v195
	v_cvt_pk_bf16_f32 v187, v66, v67
	v_cvt_pk_bf16_f32 v189, v64, v65
	v_cvt_pk_bf16_f32 v64, v202, v203
	v_cvt_pk_bf16_f32 v65, v196, v197
	v_cvt_pk_bf16_f32 v66, v204, v205
	v_cvt_pk_bf16_f32 v67, v192, v193
	v_pk_mul_f32 v[62:63], v[190:191], v[182:183]
	v_pk_mul_f32 v[60:61], v[158:159], v[180:181]
	v_pk_mul_f32 v[50:51], v[104:105], v[100:101]
	v_pk_mul_f32 v[102:103], v[54:55], v[110:111]
	v_pk_mul_f32 v[100:101], v[48:49], v[108:109]
	ds_read_b128 v[104:107], v171 offset:34816
	ds_read_b128 v[108:111], v171 offset:34880
	ds_read_b128 v[180:183], v171 offset:37120
	ds_read_b128 v[190:193], v171 offset:37184
	ds_read_b128 v[194:197], v171 offset:39424
	ds_read_b128 v[198:201], v171 offset:39488
	ds_read_b128 v[202:205], v171 offset:41728
	ds_read_b128 v[206:209], v171 offset:41792
	s_waitcnt lgkmcnt(14)
; template <bool PROMPT>
; __device__ __forceinline__ void scan_block(const Params& p, LAS unsigned char* lds, int chs0, int nsteps, const float* s0, float* sfin, int rowbase, int ntok, int h, int half) {
;     ...
;         const LAS unsigned char* B = lds + (n & 1) * SC_BUF;
;         bf16x8 Sb[4];
; #pragma unroll
;         for (int P = 0; P < 4; ++P) Sb[P] = pack8(ST[2 * P], ST[2 * P + 1]);
;         f32x4 ws[4], qs[4];
;         bf16x8 fa[8];
; #pragma unroll
;         for (int tt = 0; tt < 4; ++tt) {
; #pragma unroll
;             for (int P = 0; P < 4; ++P) { fa[P] = *(const LAS bf16x8*)(B + SC_W + (16 * tt + fr) * 272 + (32 * P + 8 * fq) * 2);
;                                           fa[4 + P] = *(const LAS bf16x8*)(B + SC_QS + (16 * tt + fr) * 272 + (32 * P + 8 * fq) * 2); }
;             __builtin_amdgcn_sched_barrier(0);
;     ...
;         for (int tt = 0; tt < 4; ++tt)
; #pragma unroll
;             for (int u = 0; u < 2; ++u) o[tt] = mfma16(fq_[tt * 2 + u], Vb[u], o[tt]);
;         __builtin_amdgcn_sched_barrier(0);
; #pragma unroll
;         for (int T = 0; T < 4; ++T)
; #pragma unroll
;             for (int u = 0; u < 2; ++u) fq_[T * 2 + u] = *(const LAS bf16x8*)(B + SC_KT + (16 * (4 + T) + fr) * 144 + (32 * u + 8 * fq) * 2);
;         __builtin_amdgcn_sched_barrier(0);
; #pragma unroll
;         for (int T = 0; T < 4; ++T)
; #pragma unroll
;             for (int u = 0; u < 2; ++u) ST[T] = mfma16(fk[T * 2 + u], Vd[u], ST[T]);
;         __builtin_amdgcn_sched_barrier(0);
; #pragma unroll
;         for (int T = 0; T < 4; ++T)
; #pragma unroll
;             for (int u = 0; u < 2; ++u) ST[4 + T] = mfma16(fq_[T * 2 + u], Vd[u], ST[4 + T]);
; #pragma unroll
;         for (int tt = 0; tt < 4; ++tt)
; #pragma unroll
;             for (int jj = 0; jj < 4; ++jj) {
;                 const int tok = 16 * tt + 4 * fq + jj;
;                 if constexpr (PROMPT) {
;                     const unsigned row = (unsigned)(rowbase + n * 64 + tok);
;                     CAT[row * (unsigned)DM + (unsigned)(512 + h * 128 + dv)] = f2bf(o[tt][jj]);
;                 } else {
;                     const unsigned row = (unsigned)(rowbase + n * 64 + (tok < ntok ? tok : 0));
;                     if (tok < ntok) CAT[row * (unsigned)DM + (unsigned)(512 + h * 128 + dv)] = f2bf(o[tt][jj]);
;                 }
;             }
;         SC_BAR();
	v_mfma_f32_16x16x32_bf16 v[54:57], v[68:71], v[172:175], v[56:59]
	s_waitcnt lgkmcnt(13)
	v_mfma_f32_16x16x32_bf16 v[58:61], v[76:79], v[172:175], v[60:63]
	s_waitcnt lgkmcnt(11)
	v_mfma_f32_16x16x32_bf16 v[48:51], v[84:87], v[172:175], v[50:53]
	s_waitcnt lgkmcnt(9)
	v_mfma_f32_16x16x32_bf16 v[68:71], v[92:95], v[172:175], v[100:103]
	v_mfma_f32_16x16x32_bf16 v[54:57], v[72:75], v[186:189], v[54:57]
	v_mfma_f32_16x16x32_bf16 v[58:61], v[80:83], v[186:189], v[58:61]
	v_mfma_f32_16x16x32_bf16 v[48:51], v[88:91], v[186:189], v[48:51]
	s_waitcnt lgkmcnt(8)
	v_mfma_f32_16x16x32_bf16 v[68:71], v[96:99], v[186:189], v[68:71]
	ds_read_b128 v[72:75], v171 offset:44032
	ds_read_b128 v[76:79], v171 offset:44096
	ds_read_b128 v[80:83], v171 offset:46336
	ds_read_b128 v[84:87], v171 offset:46400
	ds_read_b128 v[88:91], v171 offset:48640
	ds_read_b128 v[92:95], v171 offset:48704
	ds_read_b128 v[96:99], v171 offset:50944
	ds_read_b128 v[100:103], v171 offset:51008
	s_waitcnt lgkmcnt(14)
	v_mfma_f32_16x16x32_bf16 v[28:31], v[104:107], v[176:179], v[28:31]
	s_waitcnt lgkmcnt(13)
	v_mfma_f32_16x16x32_bf16 v[24:27], v[180:183], v[176:179], v[24:27]
	s_waitcnt lgkmcnt(11)
	v_mfma_f32_16x16x32_bf16 v[20:23], v[194:197], v[176:179], v[20:23]
	s_waitcnt lgkmcnt(9)
	v_mfma_f32_16x16x32_bf16 v[16:19], v[202:205], v[176:179], v[16:19]
	v_mfma_f32_16x16x32_bf16 v[28:31], v[108:111], v[64:67], v[28:31]
	v_mfma_f32_16x16x32_bf16 v[24:27], v[190:193], v[64:67], v[24:27]
	v_mfma_f32_16x16x32_bf16 v[20:23], v[198:201], v[64:67], v[20:23]
	s_waitcnt lgkmcnt(8)
	v_mfma_f32_16x16x32_bf16 v[16:19], v[206:209], v[64:67], v[16:19]
	s_waitcnt lgkmcnt(7)
	v_mfma_f32_16x16x32_bf16 v[44:47], v[72:75], v[176:179], v[44:47]
	v_cvt_pk_bf16_f32 v104, v54, s0
	v_cvt_pk_bf16_f32 v110, v50, s0
	s_waitcnt lgkmcnt(5)
	v_mfma_f32_16x16x32_bf16 v[40:43], v[80:83], v[176:179], v[40:43]
	v_cvt_pk_bf16_f32 v120, v68, s0
	v_cvt_pk_bf16_f32 v158, v69, s0
	s_waitcnt lgkmcnt(3)
	v_mfma_f32_16x16x32_bf16 v[36:39], v[88:91], v[176:179], v[36:39]
	v_cvt_pk_bf16_f32 v105, v55, s0
	s_waitcnt lgkmcnt(1)
	v_mfma_f32_16x16x32_bf16 v[32:35], v[96:99], v[176:179], v[32:35]
	v_cvt_pk_bf16_f32 v106, v56, s0
	v_cvt_pk_bf16_f32 v107, v57, s0
	v_cvt_pk_bf16_f32 v108, v58, s0
	v_cvt_pk_bf16_f32 v109, v59, s0
	v_cvt_pk_bf16_f32 v96, v60, s0
	v_cvt_pk_bf16_f32 v97, v61, s0
	v_cvt_pk_bf16_f32 v98, v48, s0
	v_cvt_pk_bf16_f32 v99, v49, s0
	v_cvt_pk_bf16_f32 v111, v51, s0
	v_cvt_pk_bf16_f32 v159, v70, s0
	v_cvt_pk_bf16_f32 v171, v71, s0
	global_store_short v152, v104, s[96:97]
	global_store_short v150, v105, s[96:97]
	global_store_short v148, v106, s[96:97]
	global_store_short v146, v107, s[96:97]
	global_store_short v144, v108, s[96:97]
	global_store_short v142, v109, s[96:97]
	global_store_short v140, v96, s[96:97]
	global_store_short v138, v97, s[96:97]
	global_store_short v136, v98, s[96:97]
	global_store_short v134, v99, s[96:97]
	v_mfma_f32_16x16x32_bf16 v[44:47], v[76:79], v[64:67], v[44:47]
	global_store_short v132, v110, s[96:97]
	global_store_short v130, v111, s[96:97]
	global_store_short v128, v120, s[96:97]
	global_store_short v126, v158, s[96:97]
	global_store_short v124, v159, s[96:97]
	global_store_short v122, v171, s[96:97]
	s_add_u32 s4, s4, 0x100
	v_mfma_f32_16x16x32_bf16 v[40:43], v[84:87], v[64:67], v[40:43]
	s_waitcnt lgkmcnt(0)
	s_barrier
	v_mfma_f32_16x16x32_bf16 v[36:39], v[92:95], v[64:67], v[36:39]
	s_addc_u32 s14, s14, 0
	s_add_u32 s96, s96, s6
	s_addc_u32 s97, s97, s7
	s_waitcnt lgkmcnt(0)
	v_mfma_f32_16x16x32_bf16 v[32:35], v[100:103], v[64:67], v[32:35]
	v_lshl_add_u64 v[154:155], v[154:155], 0, s[8:9]
	v_lshl_add_u64 v[156:157], v[156:157], 0, s[10:11]
	s_cmp_eq_u32 s16, 31
	s_mov_b32 s5, s16
	s_cbranch_scc0 .LBB0_602
	s_lshl_b32 s4, s33, 8
	s_and_b32 s4, s4, 0x3800
	s_lshl_b32 s0, s0, 16
	s_add_u32 s0, s48, s0
	v_or_b32_e32 v48, s1, v160
	s_addc_u32 s1, s49, 0
	v_or_b32_e32 v132, s4, v170
	s_add_u32 s4, s0, 0x4300000
	v_lshlrev_b32_e32 v133, 1, v48
	s_addc_u32 s5, s1, 0
	s_add_i32 s0, 0, 0x13800
	v_add3_u32 v124, 0, v169, v163
	v_add3_u32 v88, s0, v169, v163
	ds_read_b128 v[60:63], v124 offset:62464
	ds_read_b128 v[64:67], v124 offset:62528
	ds_read_b128 v[68:71], v88
	ds_read_b128 v[72:75], v88 offset:64
	ds_read_b128 v[76:79], v124 offset:62592
	ds_read_b128 v[80:83], v124 offset:62656
	ds_read_b128 v[84:87], v88 offset:128
	ds_read_b128 v[88:91], v88 offset:192
	v_cvt_pk_bf16_f32 v48, v28, v29
	v_cvt_pk_bf16_f32 v49, v30, v31
	v_cvt_pk_bf16_f32 v50, v24, v25
	v_cvt_pk_bf16_f32 v51, v26, v27
	v_cvt_pk_bf16_f32 v52, v20, v21
	v_cvt_pk_bf16_f32 v53, v22, v23
	v_cvt_pk_bf16_f32 v54, v16, v17
	v_cvt_pk_bf16_f32 v55, v18, v19
	v_cvt_pk_bf16_f32 v56, v44, v45
	v_cvt_pk_bf16_f32 v57, v46, v47
	v_cvt_pk_bf16_f32 v58, v40, v41
	v_cvt_pk_bf16_f32 v59, v42, v43
	v_cvt_pk_bf16_f32 v92, v36, v37
	v_cvt_pk_bf16_f32 v93, v38, v39
	v_cvt_pk_bf16_f32 v94, v32, v33
	v_cvt_pk_bf16_f32 v95, v34, v35
	s_waitcnt lgkmcnt(7)
	v_mfma_f32_16x16x32_bf16 v[60:63], v[60:63], v[48:51], 0
	s_waitcnt lgkmcnt(5)
	v_mfma_f32_16x16x32_bf16 v[68:71], v[68:71], v[48:51], 0
	v_mfma_f32_16x16x32_bf16 v[60:63], v[64:67], v[52:55], v[60:63]
	s_waitcnt lgkmcnt(4)
	v_mfma_f32_16x16x32_bf16 v[64:67], v[72:75], v[52:55], v[68:71]
	s_waitcnt lgkmcnt(3)
	v_mfma_f32_16x16x32_bf16 v[60:63], v[76:79], v[56:59], v[60:63]
	s_waitcnt lgkmcnt(1)
	v_mfma_f32_16x16x32_bf16 v[64:67], v[84:87], v[56:59], v[64:67]
	v_mfma_f32_16x16x32_bf16 v[96:99], v[80:83], v[92:95], v[60:63]
	s_waitcnt lgkmcnt(0)
; #define LAS __attribute__((address_space(3)))
; __device__ __forceinline__ float bf2f(short b) { return __uint_as_float(((unsigned)(unsigned short)b) << 16); }
; __device__ __forceinline__ f32x4 mfma16(const bf16x8& a, const bf16x8& b, const f32x4& c) { return __builtin_amdgcn_mfma_f32_16x16x32_bf16(a, b, c, 0, 0, 0); }
; template <bool PROMPT>
; __device__ __forceinline__ void scan_block(const Params& p, LAS unsigned char* lds, int chs0, int nsteps, const float* s0, float* sfin, int rowbase, int ntok, int h, int half) {
;     ...
;         for (int tt = 0; tt < 4; ++tt) {
; #pragma unroll
;             for (int P = 0; P < 4; ++P) { fa[P] = *(const LAS bf16x8*)(B + SC_W + (16 * tt + fr) * 272 + (32 * P + 8 * fq) * 2);
;                                           fa[4 + P] = *(const LAS bf16x8*)(B + SC_QS + (16 * tt + fr) * 272 + (32 * P + 8 * fq) * 2); }
;             __builtin_amdgcn_sched_barrier(0);
;             ws[tt] = (f32x4){0.f, 0.f, 0.f, 0.f}; qs[tt] = (f32x4){0.f, 0.f, 0.f, 0.f};
; #pragma unroll
;             for (int P = 0; P < 4; ++P) { ws[tt] = mfma16(fa[P], Sb[P], ws[tt]); qs[tt] = mfma16(fa[4 + P], Sb[P], qs[tt]); }
;             __builtin_amdgcn_sched_barrier(0);
;         }
;         bf16x8 fq_[8], fk[8];
; #pragma unroll
;         for (int tt = 0; tt < 4; ++tt)
; #pragma unroll
;             for (int u = 0; u < 2; ++u) fq_[tt * 2 + u] = *(const LAS bf16x8*)(B + SC_QK + (16 * tt + fr) * 144 + (32 * u + 8 * fq) * 2);
;         __builtin_amdgcn_sched_barrier(0);
;         f32x4 vn[4], vd[4];
; #pragma unroll
;         for (int tt = 0; tt < 4; ++tt)
; #pragma unroll
;             for (int jj = 0; jj < 4; ++jj) { vn[tt][jj] = bf2f(u4[tt][jj]) - ws[tt][jj]; vd[tt][jj] = vn[tt][jj] * __expf(Glc - g4[tt][jj]); }
	v_mfma_f32_16x16x32_bf16 v[84:87], v[88:91], v[92:95], v[64:67]
	v_add_u32_e32 v80, 0x1100, v124
	v_add3_u32 v100, s0, v168, v163
	s_nop 0
	ds_read_b128 v[60:63], v80 offset:62464
	s_nop 0
	ds_read_b128 v[64:67], v80 offset:62528
	ds_read_b128 v[68:71], v100
	ds_read_b128 v[72:75], v100 offset:64
	ds_read_b128 v[76:79], v80 offset:62592
	ds_read_b128 v[80:83], v80 offset:62656
	ds_read_b128 v[88:91], v100 offset:128
	ds_read_b128 v[100:103], v100 offset:192
	s_waitcnt lgkmcnt(7)
	v_mfma_f32_16x16x32_bf16 v[60:63], v[60:63], v[48:51], 0
	s_waitcnt lgkmcnt(5)
	v_mfma_f32_16x16x32_bf16 v[68:71], v[68:71], v[48:51], 0
	v_mfma_f32_16x16x32_bf16 v[60:63], v[64:67], v[52:55], v[60:63]
	s_waitcnt lgkmcnt(4)
	v_mfma_f32_16x16x32_bf16 v[64:67], v[72:75], v[52:55], v[68:71]
	s_waitcnt lgkmcnt(3)
	v_mfma_f32_16x16x32_bf16 v[60:63], v[76:79], v[56:59], v[60:63]
	s_waitcnt lgkmcnt(1)
	v_mfma_f32_16x16x32_bf16 v[64:67], v[88:91], v[56:59], v[64:67]
	v_mfma_f32_16x16x32_bf16 v[104:107], v[80:83], v[92:95], v[60:63]
	s_waitcnt lgkmcnt(0)
	v_mfma_f32_16x16x32_bf16 v[100:103], v[100:103], v[92:95], v[64:67]
	v_add_u32_e32 v80, 0x2200, v124
	v_add3_u32 v108, s0, v167, v163
	s_nop 0
	ds_read_b128 v[60:63], v80 offset:62464
	s_nop 0
	ds_read_b128 v[64:67], v80 offset:62528
	ds_read_b128 v[68:71], v108
	ds_read_b128 v[72:75], v108 offset:64
	ds_read_b128 v[76:79], v80 offset:62592
	ds_read_b128 v[80:83], v80 offset:62656
	ds_read_b128 v[88:91], v108 offset:128
	ds_read_b128 v[108:111], v108 offset:192
	s_waitcnt lgkmcnt(7)
	v_mfma_f32_16x16x32_bf16 v[60:63], v[60:63], v[48:51], 0
	s_waitcnt lgkmcnt(5)
	v_mfma_f32_16x16x32_bf16 v[68:71], v[68:71], v[48:51], 0
	v_mfma_f32_16x16x32_bf16 v[60:63], v[64:67], v[52:55], v[60:63]
	s_waitcnt lgkmcnt(4)
	v_mfma_f32_16x16x32_bf16 v[64:67], v[72:75], v[52:55], v[68:71]
	s_waitcnt lgkmcnt(3)
	v_mfma_f32_16x16x32_bf16 v[60:63], v[76:79], v[56:59], v[60:63]
	s_waitcnt lgkmcnt(1)
	v_mfma_f32_16x16x32_bf16 v[64:67], v[88:91], v[56:59], v[64:67]
	v_mfma_f32_16x16x32_bf16 v[120:123], v[80:83], v[92:95], v[60:63]
	s_waitcnt lgkmcnt(0)
	v_mfma_f32_16x16x32_bf16 v[80:83], v[108:111], v[92:95], v[64:67]
	v_add_u32_e32 v88, 0x3300, v124
	v_add3_u32 v124, s0, v166, v163
	s_nop 0
	ds_read_b128 v[60:63], v88 offset:62464
	s_nop 0
	ds_read_b128 v[64:67], v88 offset:62528
	ds_read_b128 v[68:71], v124
	ds_read_b128 v[72:75], v124 offset:64
	ds_read_b128 v[76:79], v88 offset:62592
	ds_read_b128 v[88:91], v88 offset:62656
	ds_read_b128 v[108:111], v124 offset:128
	ds_read_b128 v[124:127], v124 offset:192
	s_waitcnt lgkmcnt(7)
	v_mfma_f32_16x16x32_bf16 v[60:63], v[60:63], v[48:51], 0
	s_waitcnt lgkmcnt(5)
	v_mfma_f32_16x16x32_bf16 v[48:51], v[68:71], v[48:51], 0
	v_mfma_f32_16x16x32_bf16 v[60:63], v[64:67], v[52:55], v[60:63]
	s_waitcnt lgkmcnt(4)
	v_mfma_f32_16x16x32_bf16 v[48:51], v[72:75], v[52:55], v[48:51]
	s_waitcnt lgkmcnt(3)
	v_mfma_f32_16x16x32_bf16 v[52:55], v[76:79], v[56:59], v[60:63]
	s_waitcnt lgkmcnt(1)
	v_mfma_f32_16x16x32_bf16 v[48:51], v[108:111], v[56:59], v[48:51]
	v_mfma_f32_16x16x32_bf16 v[108:111], v[88:91], v[92:95], v[52:55]
	s_waitcnt lgkmcnt(0)
	v_mfma_f32_16x16x32_bf16 v[88:91], v[124:127], v[92:95], v[48:51]
	s_add_i32 s0, 0, 0x1c400
	v_add3_u32 v76, s0, v163, v164
	s_nop 2
	ds_read_b128 v[48:51], v76
	ds_read_b128 v[52:55], v76 offset:64
	ds_read_b128 v[56:59], v76 offset:2304
	ds_read_b128 v[60:63], v76 offset:2368
	ds_read_b128 v[64:67], v76 offset:4608
	ds_read_b128 v[68:71], v76 offset:4672
	ds_read_b128 v[72:75], v76 offset:6912
	ds_read_b128 v[76:79], v76 offset:6976
	s_waitcnt vmcnt(16)
	v_sub_f32_e32 v92, v165, v12
	v_sub_f32_e32 v93, v165, v13
	v_mul_f32_e32 v92, 0x3fb8aa3b, v92
	v_mul_f32_e32 v93, 0x3fb8aa3b, v93
	v_exp_f32_e32 v92, v92
	v_exp_f32_e32 v93, v93
	v_and_b32_e32 v95, 0xffff0000, v118
	v_lshlrev_b32_e32 v94, 16, v118
	v_pk_add_f32 v[94:95], v[94:95], v[96:97] neg_lo:[0,1] neg_hi:[0,1]
	v_and_b32_e32 v125, 0xffff0000, v119
	v_pk_mul_f32 v[96:97], v[92:93], v[94:95]
	v_sub_f32_e32 v92, v165, v14
	v_sub_f32_e32 v93, v165, v15
	v_mul_f32_e32 v92, 0x3fb8aa3b, v92
	v_mul_f32_e32 v93, 0x3fb8aa3b, v93
	v_exp_f32_e32 v92, v92
	v_exp_f32_e32 v93, v93
	v_lshlrev_b32_e32 v124, 16, v119
	v_pk_add_f32 v[98:99], v[124:125], v[98:99] neg_lo:[0,1] neg_hi:[0,1]
	v_and_b32_e32 v125, 0xffff0000, v116
	v_pk_mul_f32 v[118:119], v[92:93], v[98:99]
	v_sub_f32_e32 v92, v165, v8
	v_sub_f32_e32 v93, v165, v9
	v_mul_f32_e32 v92, 0x3fb8aa3b, v92
	v_mul_f32_e32 v93, 0x3fb8aa3b, v93
	v_exp_f32_e32 v92, v92
	v_exp_f32_e32 v93, v93
	v_lshlrev_b32_e32 v124, 16, v116
	v_pk_add_f32 v[104:105], v[124:125], v[104:105] neg_lo:[0,1] neg_hi:[0,1]
	v_and_b32_e32 v127, 0xffff0000, v117
	v_pk_mul_f32 v[124:125], v[92:93], v[104:105]
	v_sub_f32_e32 v92, v165, v10
	v_sub_f32_e32 v93, v165, v11
	v_mul_f32_e32 v92, 0x3fb8aa3b, v92
	v_mul_f32_e32 v93, 0x3fb8aa3b, v93
	v_exp_f32_e32 v92, v92
	v_exp_f32_e32 v93, v93
	v_lshlrev_b32_e32 v126, 16, v117
	v_pk_add_f32 v[106:107], v[126:127], v[106:107] neg_lo:[0,1] neg_hi:[0,1]
	v_and_b32_e32 v127, 0xffff0000, v114
	v_pk_mul_f32 v[116:117], v[92:93], v[106:107]
	v_sub_f32_e32 v92, v165, v4
	v_sub_f32_e32 v93, v165, v5
	v_mul_f32_e32 v92, 0x3fb8aa3b, v92
	v_mul_f32_e32 v93, 0x3fb8aa3b, v93
	v_exp_f32_e32 v92, v92
	v_exp_f32_e32 v93, v93
	v_lshlrev_b32_e32 v126, 16, v114
	v_pk_add_f32 v[120:121], v[126:127], v[120:121] neg_lo:[0,1] neg_hi:[0,1]
	v_and_b32_e32 v129, 0xffff0000, v115
	v_pk_mul_f32 v[126:127], v[92:93], v[120:121]
	v_sub_f32_e32 v92, v165, v6
	v_sub_f32_e32 v93, v165, v7
	v_mul_f32_e32 v92, 0x3fb8aa3b, v92
	v_mul_f32_e32 v93, 0x3fb8aa3b, v93
	v_exp_f32_e32 v92, v92
	v_exp_f32_e32 v93, v93
; #define LAS __attribute__((address_space(3)))
; __device__ __forceinline__ float bf2f(short b) { return __uint_as_float(((unsigned)(unsigned short)b) << 16); }
; __device__ __forceinline__ f32x4 mfma16(const bf16x8& a, const bf16x8& b, const f32x4& c) { return __builtin_amdgcn_mfma_f32_16x16x32_bf16(a, b, c, 0, 0, 0); }
; template <bool PROMPT>
; __device__ __forceinline__ void scan_block(const Params& p, LAS unsigned char* lds, int chs0, int nsteps, const float* s0, float* sfin, int rowbase, int ntok, int h, int half) {
;     ...
;             for (int jj = 0; jj < 4; ++jj) { vn[tt][jj] = bf2f(u4[tt][jj]) - ws[tt][jj]; vd[tt][jj] = vn[tt][jj] * __expf(Glc - g4[tt][jj]); }
;         bf16x8 Vb[2], Vd[2];
; #pragma unroll
;         for (int u = 0; u < 2; ++u) { Vb[u] = pack8(vn[2 * u], vn[2 * u + 1]); Vd[u] = pack8(vd[2 * u], vd[2 * u + 1]); }
;         f32x4 o[4];
; #pragma unroll
;         for (int tt = 0; tt < 4; ++tt)
; #pragma unroll
;             for (int jj = 0; jj < 4; ++jj) o[tt][jj] = qs[tt][jj] * __expf(g4[tt][jj]);
;         const float gt = __expf(Glc);
; #pragma unroll
;         for (int T = 0; T < 8; ++T) ST[T] = ST[T] * gt;
;         __builtin_amdgcn_sched_barrier(0);
; #pragma unroll
;         for (int T = 0; T < 4; ++T)
; #pragma unroll
;             for (int u = 0; u < 2; ++u) fk[T * 2 + u] = *(const LAS bf16x8*)(B + SC_KT + (16 * T + fr) * 144 + (32 * u + 8 * fq) * 2);
;         __builtin_amdgcn_sched_barrier(0);
; #pragma unroll
;         for (int tt = 0; tt < 4; ++tt)
; #pragma unroll
;             for (int u = 0; u < 2; ++u) o[tt] = mfma16(fq_[tt * 2 + u], Vb[u], o[tt]);
;         __builtin_amdgcn_sched_barrier(0);
; #pragma unroll
;         for (int T = 0; T < 4; ++T)
; #pragma unroll
;             for (int u = 0; u < 2; ++u) fq_[T * 2 + u] = *(const LAS bf16x8*)(B + SC_KT + (16 * (4 + T) + fr) * 144 + (32 * u + 8 * fq) * 2);
;         __builtin_amdgcn_sched_barrier(0);
; #pragma unroll
;         for (int T = 0; T < 4; ++T)
; #pragma unroll
;             for (int u = 0; u < 2; ++u) ST[T] = mfma16(fk[T * 2 + u], Vd[u], ST[T]);
;         __builtin_amdgcn_sched_barrier(0);
; #pragma unroll
;         for (int T = 0; T < 4; ++T)
; #pragma unroll
;             for (int u = 0; u < 2; ++u) ST[4 + T] = mfma16(fq_[T * 2 + u], Vd[u], ST[4 + T]);
	v_lshlrev_b32_e32 v128, 16, v115
	v_pk_add_f32 v[114:115], v[128:129], v[122:123] neg_lo:[0,1] neg_hi:[0,1]
	v_and_b32_e32 v129, 0xffff0000, v112
	v_pk_mul_f32 v[122:123], v[92:93], v[114:115]
	v_sub_f32_e32 v92, v165, v0
	v_sub_f32_e32 v93, v165, v1
	v_mul_f32_e32 v92, 0x3fb8aa3b, v92
	v_mul_f32_e32 v93, 0x3fb8aa3b, v93
	v_exp_f32_e32 v92, v92
	v_exp_f32_e32 v93, v93
	v_lshlrev_b32_e32 v128, 16, v112
	v_pk_add_f32 v[108:109], v[128:129], v[108:109] neg_lo:[0,1] neg_hi:[0,1]
	v_and_b32_e32 v131, 0xffff0000, v113
	v_pk_mul_f32 v[128:129], v[92:93], v[108:109]
	v_sub_f32_e32 v92, v165, v2
	v_sub_f32_e32 v93, v165, v3
	v_mul_f32_e32 v92, 0x3fb8aa3b, v92
	v_mul_f32_e32 v93, 0x3fb8aa3b, v93
	v_exp_f32_e32 v92, v92
	v_exp_f32_e32 v93, v93
	v_lshlrev_b32_e32 v130, 16, v113
	v_mul_f32_e32 v12, 0x3fb8aa3b, v12
	v_mul_f32_e32 v13, 0x3fb8aa3b, v13
	v_pk_add_f32 v[110:111], v[130:131], v[110:111] neg_lo:[0,1] neg_hi:[0,1]
	v_exp_f32_e32 v12, v12
	v_exp_f32_e32 v13, v13
	v_mul_f32_e32 v6, 0x3fb8aa3b, v6
	v_mul_f32_e32 v7, 0x3fb8aa3b, v7
	v_pk_mul_f32 v[112:113], v[92:93], v[110:111]
	v_mul_f32_e32 v8, 0x3fb8aa3b, v8
	v_exp_f32_e32 v6, v6
	v_exp_f32_e32 v7, v7
	v_cvt_pk_bf16_f32 v92, v94, v95
	v_cvt_pk_bf16_f32 v95, v106, v107
	v_cvt_pk_bf16_f32 v107, v110, v111
	v_cvt_pk_bf16_f32 v111, v112, v113
	v_mul_f32_e32 v14, 0x3fb8aa3b, v14
	v_mul_f32_e32 v15, 0x3fb8aa3b, v15
	v_exp_f32_e32 v112, v8
	v_mul_f32_e32 v8, 0x3fb8aa3b, v9
	v_mul_f32_e32 v9, 0x3fb8aa3b, v10
	v_cvt_pk_bf16_f32 v94, v104, v105
	v_cvt_pk_bf16_f32 v105, v114, v115
	v_exp_f32_e32 v14, v14
	v_exp_f32_e32 v15, v15
	v_exp_f32_e32 v114, v9
	v_mul_f32_e32 v9, 0x3fb8aa3b, v11
	v_mul_f32_e32 v4, 0x3fb8aa3b, v4
	v_exp_f32_e32 v115, v9
	v_exp_f32_e32 v113, v8
	v_pk_mul_f32 v[8:9], v[12:13], v[84:85]
	v_exp_f32_e32 v84, v4
	v_mul_f32_e32 v4, 0x3fb8aa3b, v5
	v_mul_f32_e32 v2, 0x3fb8aa3b, v2
	v_exp_f32_e32 v85, v4
	v_pk_mul_f32 v[4:5], v[6:7], v[82:83]
	v_exp_f32_e32 v6, v2
	v_mul_f32_e32 v2, 0x3fb8aa3b, v3
	v_mul_f32_e32 v0, 0x3fb8aa3b, v0
	v_mul_f32_e32 v1, 0x3fb8aa3b, v1
	v_exp_f32_e32 v7, v2
	v_mul_f32_e32 v2, 0x3fb8aa3b, v165
	v_pk_mul_f32 v[10:11], v[14:15], v[86:87]
	v_exp_f32_e32 v0, v0
	v_exp_f32_e32 v1, v1
	v_exp_f32_e32 v86, v2
	v_cvt_pk_bf16_f32 v93, v98, v99
	v_cvt_pk_bf16_f32 v96, v96, v97
	v_cvt_pk_bf16_f32 v97, v118, v119
	v_cvt_pk_bf16_f32 v98, v124, v125
	v_cvt_pk_bf16_f32 v99, v116, v117
	v_cvt_pk_bf16_f32 v104, v120, v121
	v_cvt_pk_bf16_f32 v106, v108, v109
	v_cvt_pk_bf16_f32 v108, v126, v127
	v_cvt_pk_bf16_f32 v109, v122, v123
	v_cvt_pk_bf16_f32 v110, v128, v129
	v_pk_mul_f32 v[14:15], v[114:115], v[102:103]
	v_pk_mul_f32 v[12:13], v[112:113], v[100:101]
	v_pk_mul_f32 v[2:3], v[84:85], v[80:81]
	v_pk_mul_f32 v[82:83], v[6:7], v[90:91]
	v_pk_mul_f32 v[80:81], v[0:1], v[88:89]
	v_pk_mul_f32 v[30:31], v[86:87], v[30:31] op_sel_hi:[0,1]
	v_pk_mul_f32 v[28:29], v[86:87], v[28:29] op_sel_hi:[0,1]
	v_pk_mul_f32 v[26:27], v[86:87], v[26:27] op_sel_hi:[0,1]
	v_pk_mul_f32 v[24:25], v[86:87], v[24:25] op_sel_hi:[0,1]
	v_pk_mul_f32 v[22:23], v[86:87], v[22:23] op_sel_hi:[0,1]
	v_pk_mul_f32 v[20:21], v[86:87], v[20:21] op_sel_hi:[0,1]
	v_pk_mul_f32 v[18:19], v[86:87], v[18:19] op_sel_hi:[0,1]
	v_pk_mul_f32 v[16:17], v[86:87], v[16:17] op_sel_hi:[0,1]
	v_pk_mul_f32 v[46:47], v[86:87], v[46:47] op_sel_hi:[0,1]
	v_pk_mul_f32 v[44:45], v[86:87], v[44:45] op_sel_hi:[0,1]
	v_pk_mul_f32 v[42:43], v[86:87], v[42:43] op_sel_hi:[0,1]
	v_pk_mul_f32 v[40:41], v[86:87], v[40:41] op_sel_hi:[0,1]
	v_pk_mul_f32 v[38:39], v[86:87], v[38:39] op_sel_hi:[0,1]
	v_pk_mul_f32 v[36:37], v[86:87], v[36:37] op_sel_hi:[0,1]
	v_pk_mul_f32 v[34:35], v[86:87], v[34:35] op_sel_hi:[0,1]
	v_pk_mul_f32 v[32:33], v[86:87], v[32:33] op_sel_hi:[0,1]
	s_add_i32 s0, 0, 0x17c00
	v_add3_u32 v0, s0, v163, v164
	ds_read_b128 v[84:87], v0
	ds_read_b128 v[88:91], v0 offset:64
	ds_read_b128 v[100:103], v0 offset:2304
	ds_read_b128 v[112:115], v0 offset:2368
	ds_read_b128 v[116:119], v0 offset:4608
	ds_read_b128 v[120:123], v0 offset:4672
	ds_read_b128 v[124:127], v0 offset:6912
	ds_read_b128 v[128:131], v0 offset:6976
	s_waitcnt lgkmcnt(14)
	v_mfma_f32_16x16x32_bf16 v[6:9], v[48:51], v[92:95], v[8:11]
	s_waitcnt lgkmcnt(13)
	v_mfma_f32_16x16x32_bf16 v[10:13], v[56:59], v[92:95], v[12:15]
	s_waitcnt lgkmcnt(11)
	v_mfma_f32_16x16x32_bf16 v[0:3], v[64:67], v[92:95], v[2:5]
	s_waitcnt lgkmcnt(9)
	v_mfma_f32_16x16x32_bf16 v[48:51], v[72:75], v[92:95], v[80:83]
	v_mfma_f32_16x16x32_bf16 v[6:9], v[52:55], v[104:107], v[6:9]
	v_mfma_f32_16x16x32_bf16 v[10:13], v[60:63], v[104:107], v[10:13]
	v_mfma_f32_16x16x32_bf16 v[0:3], v[68:71], v[104:107], v[0:3]
	s_waitcnt lgkmcnt(8)
	v_mfma_f32_16x16x32_bf16 v[48:51], v[76:79], v[104:107], v[48:51]
	s_add_i32 s0, 0, 0x1a000
	v_add3_u32 v4, s0, v163, v164
	ds_read_b128 v[52:55], v4
	ds_read_b128 v[56:59], v4 offset:64
	ds_read_b128 v[60:63], v4 offset:2304
	ds_read_b128 v[64:67], v4 offset:2368
	ds_read_b128 v[68:71], v4 offset:4608
	ds_read_b128 v[72:75], v4 offset:4672
	ds_read_b128 v[76:79], v4 offset:6912
	ds_read_b128 v[80:83], v4 offset:6976
	s_waitcnt lgkmcnt(14)
	v_mfma_f32_16x16x32_bf16 v[28:31], v[84:87], v[96:99], v[28:31]
	s_waitcnt lgkmcnt(13)
	v_mfma_f32_16x16x32_bf16 v[24:27], v[100:103], v[96:99], v[24:27]
	s_waitcnt lgkmcnt(11)
	v_mfma_f32_16x16x32_bf16 v[20:23], v[116:119], v[96:99], v[20:23]
	s_waitcnt lgkmcnt(9)
	v_mfma_f32_16x16x32_bf16 v[14:17], v[124:127], v[96:99], v[16:19]
	v_mfma_f32_16x16x32_bf16 v[28:31], v[88:91], v[108:111], v[28:31]
	v_mfma_f32_16x16x32_bf16 v[24:27], v[112:115], v[108:111], v[24:27]
	v_mfma_f32_16x16x32_bf16 v[20:23], v[120:123], v[108:111], v[20:23]
	s_waitcnt lgkmcnt(8)
; __device__ __forceinline__ bf16_t f2bf(float f) { return (bf16_t)(cvt_pk_bf16(f, 0.f) & 0xffffu); }
; __device__ __forceinline__ f32x4 mfma16(const bf16x8& a, const bf16x8& b, const f32x4& c) { return __builtin_amdgcn_mfma_f32_16x16x32_bf16(a, b, c, 0, 0, 0); }
; #define SC_BAR() do { asm volatile("s_waitcnt lgkmcnt(0)" ::: "memory"); __builtin_amdgcn_s_barrier(); asm volatile("" ::: "memory"); } while (0)
; template <bool PROMPT>
; __device__ __forceinline__ void scan_block(const Params& p, LAS unsigned char* lds, int chs0, int nsteps, const float* s0, float* sfin, int rowbase, int ntok, int h, int half) {
;     ...
;         for (int T = 0; T < 4; ++T)
; #pragma unroll
;             for (int u = 0; u < 2; ++u) ST[T] = mfma16(fk[T * 2 + u], Vd[u], ST[T]);
;         __builtin_amdgcn_sched_barrier(0);
; #pragma unroll
;         for (int T = 0; T < 4; ++T)
; #pragma unroll
;             for (int u = 0; u < 2; ++u) ST[4 + T] = mfma16(fq_[T * 2 + u], Vd[u], ST[4 + T]);
; #pragma unroll
;         for (int tt = 0; tt < 4; ++tt)
; #pragma unroll
;             for (int jj = 0; jj < 4; ++jj) {
;                 const int tok = 16 * tt + 4 * fq + jj;
;                 if constexpr (PROMPT) {
;                     const unsigned row = (unsigned)(rowbase + n * 64 + tok);
;                     CAT[row * (unsigned)DM + (unsigned)(512 + h * 128 + dv)] = f2bf(o[tt][jj]);
;                 } else {
;                     const unsigned row = (unsigned)(rowbase + n * 64 + (tok < ntok ? tok : 0));
;                     if (tok < ntok) CAT[row * (unsigned)DM + (unsigned)(512 + h * 128 + dv)] = f2bf(o[tt][jj]);
;                 }
;             }
;         SC_BAR();
;     }
;     ...
; #pragma unroll
;     for (int T = 0; T < 8; ++T)
; #pragma unroll
;         for (int jj = 0; jj < 4; ++jj) sfin[(size_t)(16 * T + 4 * fq + jj) * 128 + dv] = ST[T][jj];
	v_mfma_f32_16x16x32_bf16 v[14:17], v[128:131], v[108:111], v[14:17]
	v_cvt_pk_bf16_f32 v6, v6, s0
	v_lshlrev_b32_e32 v4, 11, v132
	s_movk_i32 s0, 0x400
	v_or3_b32 v18, v133, v4, s0
	v_mov_b32_e32 v19, 0
	s_waitcnt lgkmcnt(7)
	v_mfma_f32_16x16x32_bf16 v[44:47], v[52:55], v[96:99], v[44:47]
	v_lshl_add_u64 v[52:53], s[50:51], 0, v[18:19]
	s_mov_b32 s0, 0x9f20000
	v_add_co_u32_e32 v4, vcc, s0, v52
	s_mov_b32 s0, 0x9f21000
	s_nop 0
	v_addc_co_u32_e32 v5, vcc, 0, v53, vcc
	v_add_co_u32_e32 v54, vcc, s0, v52
	v_cvt_pk_bf16_f32 v8, v8, s0
	s_nop 0
	v_addc_co_u32_e32 v55, vcc, 0, v53, vcc
	global_store_short v[54:55], v6, off offset:-4096
	v_cvt_pk_bf16_f32 v6, v7, s0
	global_store_short v[54:55], v8, off
	v_cvt_pk_bf16_f32 v8, v9, s0
	v_cvt_pk_bf16_f32 v10, v10, s0
	s_mov_b32 s0, 0x9f28000
	global_store_short v[54:55], v8, off offset:2048
	v_add_co_u32_e32 v8, vcc, s0, v52
	s_mov_b32 s0, 0x9f29000
	s_nop 0
	v_addc_co_u32_e32 v9, vcc, 0, v53, vcc
	global_store_short v[4:5], v6, off offset:2048
	s_waitcnt lgkmcnt(1)
	v_mfma_f32_16x16x32_bf16 v[4:7], v[76:79], v[96:99], v[32:35]
	v_cvt_pk_bf16_f32 v0, v0, s0
	s_nop 1
	v_add_co_u32_e32 v32, vcc, s0, v52
	v_mfma_f32_16x16x32_bf16 v[44:47], v[56:59], v[108:111], v[44:47]
	s_nop 0
	v_addc_co_u32_e32 v33, vcc, 0, v53, vcc
	global_store_short v[32:33], v10, off offset:-4096
	v_cvt_pk_bf16_f32 v10, v11, s0
	global_store_short v[8:9], v10, off offset:2048
	v_cvt_pk_bf16_f32 v8, v12, s0
	global_store_short v[32:33], v8, off
	v_cvt_pk_bf16_f32 v8, v13, s0
	s_mov_b32 s0, 0x9f30000
	global_store_short v[32:33], v8, off offset:2048
	v_add_co_u32_e32 v8, vcc, s0, v52
	s_mov_b32 s0, 0x9f31000
	s_nop 0
	v_addc_co_u32_e32 v9, vcc, 0, v53, vcc
	v_add_co_u32_e32 v10, vcc, s0, v52
	v_mfma_f32_16x16x32_bf16 v[40:43], v[60:63], v[96:99], v[40:43]
	s_nop 0
	v_addc_co_u32_e32 v11, vcc, 0, v53, vcc
	global_store_short v[10:11], v0, off offset:-4096
	v_cvt_pk_bf16_f32 v0, v1, s0
	global_store_short v[8:9], v0, off offset:2048
	v_cvt_pk_bf16_f32 v0, v2, s0
	global_store_short v[10:11], v0, off
	v_cvt_pk_bf16_f32 v0, v3, s0
	v_cvt_pk_bf16_f32 v8, v48, s0
	s_mov_b32 s0, 0x9f38000
	global_store_short v[10:11], v0, off offset:2048
	v_add_co_u32_e32 v0, vcc, s0, v52
	s_mov_b32 s0, 0x9f39000
	s_nop 0
	v_addc_co_u32_e32 v1, vcc, 0, v53, vcc
	v_add_co_u32_e32 v2, vcc, s0, v52
	v_mfma_f32_16x16x32_bf16 v[36:39], v[68:71], v[96:99], v[36:39]
	s_nop 0
	v_addc_co_u32_e32 v3, vcc, 0, v53, vcc
	global_store_short v[2:3], v8, off offset:-4096
	v_cvt_pk_bf16_f32 v8, v49, s0
	global_store_short v[0:1], v8, off offset:2048
	v_cvt_pk_bf16_f32 v0, v50, s0
	global_store_short v[2:3], v0, off
	v_cvt_pk_bf16_f32 v0, v51, s0
	global_store_short v[2:3], v0, off offset:2048
	v_lshlrev_b32_e32 v0, 2, v160
	v_lshl_or_b32 v18, v162, 11, v0
	v_lshl_add_u64 v[0:1], s[4:5], 0, v[18:19]
	s_movk_i32 s0, 0x2000
	v_add_co_u32_e32 v2, vcc, s0, v0
	s_movk_i32 s0, 0x4000
	s_nop 0
	v_addc_co_u32_e32 v3, vcc, 0, v1, vcc
	s_waitcnt lgkmcnt(0)
	s_barrier
	global_store_dword v18, v28, s[4:5]
	global_store_dword v18, v29, s[4:5] offset:512
	global_store_dword v18, v30, s[4:5] offset:1024
	global_store_dword v18, v31, s[4:5] offset:1536
	global_store_dword v[2:3], v24, off
	global_store_dword v[2:3], v25, off offset:512
	global_store_dword v[2:3], v26, off offset:1024
	global_store_dword v[2:3], v27, off offset:1536
	v_add_co_u32_e32 v2, vcc, s0, v0
	v_lshl_or_b32 v8, v161, 9, v160
	s_nop 0
	v_addc_co_u32_e32 v3, vcc, 0, v1, vcc
	v_or_b32_e32 v18, 0x1800, v8
	global_store_dword v[2:3], v20, off
	global_store_dword v[2:3], v21, off offset:512
	global_store_dword v[2:3], v22, off offset:1024
	global_store_dword v[2:3], v23, off offset:1536
	v_lshl_add_u64 v[2:3], v[18:19], 2, s[4:5]
	v_or_b32_e32 v18, 0x1880, v8
	global_store_dword v[2:3], v14, off
	v_lshl_add_u64 v[2:3], v[18:19], 2, s[4:5]
	v_or_b32_e32 v18, 0x1900, v8
	global_store_dword v[2:3], v15, off
	v_lshl_add_u64 v[2:3], v[18:19], 2, s[4:5]
	v_or_b32_e32 v18, 0x1980, v8
	global_store_dword v[2:3], v16, off
	v_lshl_add_u64 v[2:3], v[18:19], 2, s[4:5]
	s_mov_b32 s0, 0x8000
	global_store_dword v[2:3], v17, off
	v_add_co_u32_e32 v2, vcc, s0, v0
	s_mov_b32 s0, 0xa000
	s_nop 0
	v_addc_co_u32_e32 v3, vcc, 0, v1, vcc
	v_mfma_f32_16x16x32_bf16 v[40:43], v[64:67], v[108:111], v[40:43]
	global_store_dword v[2:3], v44, off
	global_store_dword v[2:3], v45, off offset:512
	global_store_dword v[2:3], v46, off offset:1024
	global_store_dword v[2:3], v47, off offset:1536
	v_add_co_u32_e32 v2, vcc, s0, v0
	v_mfma_f32_16x16x32_bf16 v[36:39], v[72:75], v[108:111], v[36:39]
	s_nop 0
	v_addc_co_u32_e32 v3, vcc, 0, v1, vcc
	s_mov_b32 s0, 0xc000
	s_waitcnt lgkmcnt(0)
	v_mfma_f32_16x16x32_bf16 v[4:7], v[80:83], v[108:111], v[4:7]
	v_add_co_u32_e32 v0, vcc, s0, v0
	v_or_b32_e32 v18, 0x3800, v8
	s_nop 0
	v_addc_co_u32_e32 v1, vcc, 0, v1, vcc
	global_store_dword v[2:3], v40, off
	global_store_dword v[2:3], v41, off offset:512
	global_store_dword v[2:3], v42, off offset:1024
	global_store_dword v[2:3], v43, off offset:1536
	global_store_dword v[0:1], v36, off
	global_store_dword v[0:1], v37, off offset:512
	global_store_dword v[0:1], v38, off offset:1024
	global_store_dword v[0:1], v39, off offset:1536
	v_lshl_add_u64 v[0:1], v[18:19], 2, s[4:5]
	v_or_b32_e32 v18, 0x3880, v8
	global_store_dword v[0:1], v4, off
	v_lshl_add_u64 v[0:1], v[18:19], 2, s[4:5]
	v_or_b32_e32 v18, 0x3900, v8
	global_store_dword v[0:1], v5, off
	v_lshl_add_u64 v[0:1], v[18:19], 2, s[4:5]
	v_or_b32_e32 v18, 0x3980, v8
	global_store_dword v[0:1], v6, off
	v_lshl_add_u64 v[0:1], v[18:19], 2, s[4:5]
	global_store_dword v[0:1], v7, off
